# attention tiles: the eight V^T fragment reads issued together behind the last QK MFMA into free registers (no LDS wait in front of each PV MFMA)
# speedup vs baseline: 1.0113x; 1.0008x over previous
.LBB0_623:
	v_add3_u32 v144, s38, v161, v162
	s_waitcnt lgkmcnt(8)
	ds_read_b128 v[80:83], v144
	s_waitcnt lgkmcnt(8)
	ds_read_b128 v[60:63], v144 offset:32
	s_waitcnt lgkmcnt(8)
	ds_read_b128 v[56:59], v144 offset:64
	s_waitcnt lgkmcnt(8)
	ds_read_b128 v[48:51], v144 offset:96
	s_waitcnt lgkmcnt(8)
	ds_read_b128 v[52:55], v144 offset:4608
	s_and_b32 s0, s89, 7
	s_cmp_eq_u32 s0, 0
	s_cbranch_scc1 .LBB0_628
	s_waitcnt lgkmcnt(4)
	v_mfma_f32_32x32x16_bf16 v[16:31], v[80:83], v[64:67], 0
	ds_read_b128 v[84:87], v144 offset:4640
	ds_read_b128 v[146:149], v144 offset:4672
	s_waitcnt lgkmcnt(5)
	v_mfma_f32_32x32x16_bf16 v[16:31], v[60:63], v[68:71], v[16:31]
	s_waitcnt lgkmcnt(2)
	v_mfma_f32_32x32x16_bf16 v[0:15], v[52:55], v[64:67], 0
	v_mfma_f32_32x32x16_bf16 v[16:31], v[56:59], v[72:75], v[16:31]
	s_waitcnt lgkmcnt(1)
	v_mfma_f32_32x32x16_bf16 v[0:15], v[84:87], v[68:71], v[0:15]
	ds_read_b128 v[84:87], v144 offset:4704
	v_mfma_f32_32x32x16_bf16 v[16:31], v[48:51], v[76:79], v[16:31]
	s_waitcnt lgkmcnt(1)
	v_mfma_f32_32x32x16_bf16 v[0:15], v[146:149], v[72:75], v[0:15]
	s_nop 9
	v_fma_f32 v16, 0, v106, v16
	v_add_f32_e32 v17, v106, v17
	v_fma_f32 v18, 2.0, v106, v18
	v_fmamk_f32 v19, v106, 0x40400000, v19
	v_fmamk_f32 v20, v106, 0x41000000, v20
	v_fmamk_f32 v21, v106, 0x41100000, v21
	v_fmamk_f32 v22, v106, 0x41200000, v22
	s_waitcnt lgkmcnt(0)
	v_mfma_f32_32x32x16_bf16 v[0:15], v[84:87], v[76:79], v[0:15]
	ds_read_b128 v[200:203], v144 offset:9216
	ds_read_b128 v[204:207], v144 offset:13824
	ds_read_b128 v[214:217], v144 offset:9248
	ds_read_b128 v[218:221], v144 offset:13856
	ds_read_b128 v[222:225], v144 offset:9280
	ds_read_b128 v[226:229], v144 offset:13888
	ds_read_b128 v[230:233], v144 offset:9312
	ds_read_b128 v[234:237], v144 offset:13920
	v_max3_f32 v85, v16, s95, v17
	v_max3_f32 v85, v85, v18, v19
	v_max3_f32 v85, v85, v20, v21
	v_fmamk_f32 v23, v106, 0x41300000, v23
	v_max3_f32 v85, v85, v22, v23
	v_fmamk_f32 v24, v106, 0x41800000, v24
	v_fmamk_f32 v25, v106, 0x41880000, v25
	v_max3_f32 v85, v85, v24, v25
	v_fmamk_f32 v26, v106, 0x41900000, v26
	v_fmamk_f32 v27, v106, 0x41980000, v27
	v_max3_f32 v85, v85, v26, v27
	v_fmamk_f32 v28, v106, 0x41c00000, v28
	v_fmamk_f32 v29, v106, 0x41c80000, v29
	v_max3_f32 v85, v85, v28, v29
	v_fmamk_f32 v30, v106, 0x41d00000, v30
	v_fmac_f32_e32 v31, 0x41d80000, v106
	v_max3_f32 v85, v85, v30, v31
	v_fmamk_f32 v0, v106, 0x42000000, v0
	v_fmamk_f32 v1, v106, 0x42040000, v1
	v_max3_f32 v85, v85, v0, v1
	v_fmamk_f32 v2, v106, 0x42080000, v2
	v_fmamk_f32 v3, v106, 0x420c0000, v3
	v_max3_f32 v85, v85, v2, v3
	v_fmamk_f32 v4, v106, 0x42200000, v4
	v_fmamk_f32 v5, v106, 0x42240000, v5
	v_or_b32_e32 v84, s8, v116
	v_max3_f32 v85, v85, v4, v5
	v_fmamk_f32 v6, v106, 0x42280000, v6
	v_fmamk_f32 v7, v106, 0x422c0000, v7
	v_sub_u32_e32 v84, v157, v84
	v_max3_f32 v85, v85, v6, v7
	v_fmamk_f32 v8, v106, 0x42400000, v8
	v_fmamk_f32 v9, v106, 0x42440000, v9
	v_cvt_f32_i32_e32 v84, v84
	v_max3_f32 v85, v85, v8, v9
	v_fmamk_f32 v10, v106, 0x42480000, v10
	v_fmamk_f32 v11, v106, 0x424c0000, v11
	v_max3_f32 v85, v85, v10, v11
	v_fmamk_f32 v12, v106, 0x42600000, v12
	v_fmamk_f32 v13, v106, 0x42640000, v13
	v_max3_f32 v85, v85, v12, v13
	v_fmamk_f32 v14, v106, 0x42680000, v14
	v_fmac_f32_e32 v15, 0x426c0000, v106
	v_max3_f32 v85, v85, v14, v15
	v_cmp_lt_f32_e32 vcc, s76, v85
	v_fma_f32 v85, -v106, v84, v85
	s_nop 0
	v_cndmask_b32_e32 v85, v160, v85, vcc
	v_mov_b32_e32 v86, v85
	s_nop 1
	v_permlane32_swap_b32_e32 v86, v85
	s_nop 1
	s_waitcnt lgkmcnt(0)
	v_max3_f32 v145, v143, v85, v86
	v_fma_f32 v84, v106, v84, v145
	v_sub_f32_e32 v16, v16, v84
	v_exp_f32_e32 v86, v16
	v_sub_f32_e32 v17, v17, v84
	v_exp_f32_e32 v87, v17
	v_sub_f32_e32 v17, v18, v84
	v_exp_f32_e32 v181, v17
	v_sub_f32_e32 v17, v19, v84
	v_exp_f32_e32 v182, v17
	v_sub_f32_e32 v17, v20, v84
	v_add_f32_e32 v16, 0, v86
	v_exp_f32_e32 v183, v17
	v_sub_f32_e32 v17, v21, v84
	v_add_f32_e32 v16, v87, v16
	v_exp_f32_e32 v184, v17
	v_sub_f32_e32 v17, v22, v84
	v_sub_f32_e32 v1, v1, v84
	v_add_f32_e32 v16, v181, v16
	v_exp_f32_e32 v185, v17
	v_sub_f32_e32 v17, v23, v84
	v_exp_f32_e32 v148, v1
	v_sub_f32_e32 v1, v2, v84
	v_add_f32_e32 v16, v182, v16
	v_exp_f32_e32 v186, v17
	v_sub_f32_e32 v17, v24, v84
	v_exp_f32_e32 v149, v1
	v_sub_f32_e32 v1, v3, v84
	v_add_f32_e32 v16, v183, v16
	v_exp_f32_e32 v172, v17
	v_sub_f32_e32 v17, v25, v84
	v_exp_f32_e32 v150, v1
	v_sub_f32_e32 v1, v4, v84
	v_add_f32_e32 v16, v184, v16
	v_exp_f32_e32 v174, v17
	v_sub_f32_e32 v17, v26, v84
	v_exp_f32_e32 v151, v1
	v_sub_f32_e32 v1, v5, v84
	v_add_f32_e32 v16, v185, v16
	v_exp_f32_e32 v175, v17
	v_sub_f32_e32 v17, v27, v84
	v_exp_f32_e32 v152, v1
	v_sub_f32_e32 v1, v6, v84
	v_add_f32_e32 v16, v186, v16
	v_exp_f32_e32 v176, v17
	v_sub_f32_e32 v17, v28, v84
	v_exp_f32_e32 v153, v1
	v_sub_f32_e32 v1, v7, v84
	v_add_f32_e32 v16, v172, v16
	v_exp_f32_e32 v177, v17
	v_sub_f32_e32 v17, v29, v84
	v_exp_f32_e32 v165, v1
	v_sub_f32_e32 v1, v8, v84
	v_add_f32_e32 v16, v174, v16
	v_exp_f32_e32 v178, v17
	v_sub_f32_e32 v17, v30, v84
	v_exp_f32_e32 v164, v1
	v_sub_f32_e32 v1, v9, v84
	v_add_f32_e32 v16, v175, v16
	v_exp_f32_e32 v179, v17
	v_sub_f32_e32 v17, v31, v84
	v_exp_f32_e32 v166, v1
	v_sub_f32_e32 v1, v10, v84
	v_add_f32_e32 v16, v176, v16
	v_exp_f32_e32 v180, v17
	v_sub_f32_e32 v0, v0, v84
	v_exp_f32_e32 v167, v1
	v_sub_f32_e32 v1, v11, v84
	v_add_f32_e32 v16, v177, v16
	v_exp_f32_e32 v147, v0
	v_exp_f32_e32 v168, v1
	v_sub_f32_e32 v1, v12, v84
	v_add_f32_e32 v16, v178, v16
	v_exp_f32_e32 v169, v1
	v_sub_f32_e32 v1, v13, v84
	v_sub_f32_e32 v85, v143, v145
	v_add_f32_e32 v16, v179, v16
	v_exp_f32_e32 v170, v1
	v_sub_f32_e32 v1, v14, v84
	v_add_f32_e32 v16, v180, v16
	v_exp_f32_e32 v171, v1
	v_sub_f32_e32 v1, v15, v84
	v_exp_f32_e32 v14, v85
	v_cvt_pk_bf16_f32 v84, v86, v87
	v_cvt_pk_bf16_f32 v85, v181, v182
	v_cvt_pk_bf16_f32 v86, v183, v184
	v_cvt_pk_bf16_f32 v87, v185, v186
	s_nop 0
	v_add_f32_e32 v0, v147, v16
	v_add_f32_e32 v0, v148, v0
	v_add_f32_e32 v0, v149, v0
	v_add_f32_e32 v0, v150, v0
	v_add_f32_e32 v0, v151, v0
	v_add_f32_e32 v0, v152, v0
	v_add_f32_e32 v0, v153, v0
	v_add_f32_e32 v0, v165, v0
	v_pk_mul_f32 v[16:17], v[108:109], v[14:15] op_sel_hi:[1,0]
	v_pk_mul_f32 v[18:19], v[110:111], v[14:15] op_sel_hi:[1,0]
	v_pk_mul_f32 v[20:21], v[112:113], v[14:15] op_sel_hi:[1,0]
	v_pk_mul_f32 v[22:23], v[114:115], v[14:15] op_sel_hi:[1,0]
	v_pk_mul_f32 v[24:25], v[118:119], v[14:15] op_sel_hi:[1,0]
	v_pk_mul_f32 v[26:27], v[120:121], v[14:15] op_sel_hi:[1,0]
	v_pk_mul_f32 v[28:29], v[122:123], v[14:15] op_sel_hi:[1,0]
	v_pk_mul_f32 v[30:31], v[124:125], v[14:15] op_sel_hi:[1,0]
	v_add_f32_e32 v0, v164, v0
	v_add_f32_e32 v0, v166, v0
	s_waitcnt lgkmcnt(0)
; #define MFMA32(a, b, c) __builtin_amdgcn_mfma_f32_32x32x16_bf16((a), (b), (c), 0, 0, 0)
; template <int KSTRIDE, bool WIN, int MASK, int MODE>
; DI void attend_tile(const u16* Ks, const u16* Vts, const bf16x8 (&qf)[4], f32x16 (&O)[2], float& m, float& l, int dbase,
;                     float slope2, bool lanesel, float invl, unsigned* imp_row, int mbase, int lr, int hh) {
;   f32x16 s[2];
; #pragma unroll
;   for (int kt = 0; kt < 2; ++kt) {
; #pragma unroll
;     for (int e = 0; e < 16; ++e) s[kt][e] = 0.f;
; #pragma unroll
;     for (int ks = 0; ks < 4; ++ks) {
;       bf16x8 a = *(const bf16x8*)(Ks + (kt * 32 + lr) * 72 + ks * 16 + hh * 8);
;       s[kt] = MFMA32(a, qf[ks], s[kt]);
;     }
;   }
;   const float fd0 = (float)(dbase - KSTRIDE * 4 * hh);
;   const float ct = slope2 * fd0;
;   float mx = -1e30f;
; #pragma unroll
;   for (int kt = 0; kt < 2; ++kt)
; #pragma unroll
;     for (int e = 0; e < 16; ++e) {
;       const float Ke = (float)(KSTRIDE * (kt * 32 + (e & 3) + 8 * (e >> 2)));
;       float v = fmaf(slope2, Ke, s[kt][e]);
;       if (MASK == 1) {
;         const float fd = fd0 - Ke;
;         bool valid = fd >= 0.f;
;         if (WIN) valid = valid && (fd < 512.f);
;         valid = valid && lanesel;
;         v = valid ? v : -1e30f;
;       }
;       s[kt][e] = v;
;       mx = fmaxf(mx, v);
;     }
;     ...
; #pragma unroll
;   for (int kt = 0; kt < 2; ++kt)
; #pragma unroll
;     for (int sx = 0; sx < 2; ++sx) {
;       unsigned pk[4];
; #pragma unroll
;       for (int q = 0; q < 4; ++q) pk[q] = pack2(s[kt][8 * sx + 2 * q], s[kt][8 * sx + 2 * q + 1]);
;       bf16x8 pb;
;       {
;         u32x4 t4 = {pk[0], pk[1], pk[2], pk[3]};
;         pb = __builtin_bit_cast(bf16x8, t4);
;       }
; #pragma unroll
;       for (int dt = 0; dt < 2; ++dt) {
;         bf16x8 a = *(const bf16x8*)(Vts + (dt * 32 + lr) * 72 + kt * 32 + 16 * sx + 8 * hh);
;         O[dt] = MFMA32(a, pb, O[dt]);
;       }
;     }
	v_mfma_f32_32x32x16_bf16 v[16:31], v[200:203], v[84:87], v[16:31]
	s_nop 0
	v_add_f32_e32 v0, v167, v0
	v_add_f32_e32 v0, v168, v0
	v_exp_f32_e32 v173, v1
	v_add_f32_e32 v0, v169, v0
	v_add_f32_e32 v0, v170, v0
	v_add_f32_e32 v0, v171, v0
	v_add_f32_e32 v146, v173, v0
	v_fmac_f32_e32 v146, v142, v14
	v_pk_mul_f32 v[0:1], v[132:133], v[14:15] op_sel_hi:[1,0]
	v_pk_mul_f32 v[2:3], v[134:135], v[14:15] op_sel_hi:[1,0]
	v_pk_mul_f32 v[4:5], v[138:139], v[14:15] op_sel_hi:[1,0]
	v_pk_mul_f32 v[6:7], v[126:127], v[14:15] op_sel_hi:[1,0]
	v_pk_mul_f32 v[8:9], v[128:129], v[14:15] op_sel_hi:[1,0]
	v_pk_mul_f32 v[10:11], v[130:131], v[14:15] op_sel_hi:[1,0]
	v_pk_mul_f32 v[12:13], v[136:137], v[14:15] op_sel_hi:[1,0]
	v_pk_mul_f32 v[14:15], v[140:141], v[14:15] op_sel_hi:[1,0]
	s_waitcnt lgkmcnt(0)
	s_nop 0
	v_mfma_f32_32x32x16_bf16 v[0:15], v[204:207], v[84:87], v[0:15]
	v_cvt_pk_bf16_f32 v84, v172, v174
	v_cvt_pk_bf16_f32 v85, v175, v176
	v_cvt_pk_bf16_f32 v86, v177, v178
	s_nop 0
	v_cvt_pk_bf16_f32 v87, v179, v180
	s_waitcnt lgkmcnt(0)
	s_nop 0
	v_mfma_f32_32x32x16_bf16 v[16:31], v[214:217], v[84:87], v[16:31]
	s_nop 0
	s_waitcnt lgkmcnt(0)
	v_mfma_f32_32x32x16_bf16 v[0:15], v[218:221], v[84:87], v[0:15]
	v_cvt_pk_bf16_f32 v84, v147, v148
	v_cvt_pk_bf16_f32 v85, v149, v150
	v_cvt_pk_bf16_f32 v86, v151, v152
	s_nop 0
	v_cvt_pk_bf16_f32 v87, v153, v165
	s_waitcnt lgkmcnt(0)
	s_nop 0
	v_mfma_f32_32x32x16_bf16 v[16:31], v[222:225], v[84:87], v[16:31]
	s_nop 0
	s_waitcnt lgkmcnt(0)
	v_mfma_f32_32x32x16_bf16 v[0:15], v[226:229], v[84:87], v[0:15]
	s_nop 0
	v_cvt_pk_bf16_f32 v84, v164, v166
	v_cvt_pk_bf16_f32 v85, v167, v168
	v_cvt_pk_bf16_f32 v86, v169, v170
	v_cvt_pk_bf16_f32 v87, v171, v173
	s_waitcnt lgkmcnt(0)
	s_nop 0
	v_mfma_f32_32x32x16_bf16 v[16:31], v[230:233], v[84:87], v[16:31]
	s_nop 0
	s_waitcnt lgkmcnt(0)
	v_mfma_f32_32x32x16_bf16 v[0:15], v[234:237], v[84:87], v[0:15]
	s_nop 7
	s_nop 3
	s_cbranch_execnz .LBB0_626
.LBB0_625:
	s_waitcnt lgkmcnt(4)
	v_mfma_f32_32x32x16_bf16 v[0:15], v[80:83], v[64:67], 0
	s_movk_i32 s0, 0x200
	s_mov_b32 s86, s85
	s_mov_b32 s38, s84
	s_mov_b32 s82, s19
	s_waitcnt lgkmcnt(3)
	v_mfma_f32_32x32x16_bf16 v[0:15], v[60:63], v[68:71], v[0:15]
	s_waitcnt lgkmcnt(2)
	v_mfma_f32_32x32x16_bf16 v[0:15], v[56:59], v[72:75], v[0:15]
	s_waitcnt lgkmcnt(0)
	v_mfma_f32_32x32x16_bf16 v[16:31], v[52:55], v[64:67], 0
	v_mfma_f32_32x32x16_bf16 v[0:15], v[48:51], v[76:79], v[0:15]
	ds_read_b128 v[48:51], v144 offset:4640
	ds_read_b128 v[56:59], v144 offset:4672
	s_waitcnt lgkmcnt(1)
	v_mfma_f32_32x32x16_bf16 v[16:31], v[48:51], v[68:71], v[16:31]
	ds_read_b128 v[50:53], v144 offset:4704
	v_or_b32_e32 v48, s8, v116
	v_sub_u32_e32 v49, v157, v48
	v_cvt_f32_i32_e32 v48, v49
	s_nop 3
	v_fma_f32 v0, 0, v106, v0
	v_cmp_gt_u32_e32 vcc, s0, v49
	v_pk_fma_f32 v[8:9], v[106:107], s[82:83], v[8:9]
	s_waitcnt lgkmcnt(1)
	v_mfma_f32_32x32x16_bf16 v[16:31], v[56:59], v[72:75], v[16:31]
	v_cndmask_b32_e32 v55, v160, v0, vcc
	v_add_f32_e32 v0, v106, v1
	v_add_f32_e32 v1, -1.0, v48
	v_cmp_le_f32_e32 vcc, 0, v1
	v_cmp_gt_f32_e64 s[0:1], s52, v1
	s_and_b64 vcc, vcc, s[0:1]
	s_mov_b32 s0, 0x42680000
	s_waitcnt lgkmcnt(0)
	v_mfma_f32_32x32x16_bf16 v[16:31], v[50:53], v[76:79], v[16:31]
	ds_read_b128 v[200:203], v144 offset:9216
	ds_read_b128 v[204:207], v144 offset:13824
	ds_read_b128 v[214:217], v144 offset:9248
	ds_read_b128 v[218:221], v144 offset:9312
	ds_read_b128 v[222:225], v144 offset:9280
	ds_read_b128 v[226:229], v144 offset:13888
	ds_read_b128 v[230:233], v144 offset:13856
	ds_read_b128 v[234:237], v144 offset:13920
	s_mov_b32 s1, 0x426c0000
	v_cndmask_b32_e32 v56, v160, v0, vcc
	v_fma_f32 v6, v106, s58, v6
	v_fma_f32 v7, v107, s59, v7
	v_max3_f32 v57, v55, s95, v56
	s_nop 6
	v_pk_fma_f32 v[0:1], v[106:107], s[0:1], v[30:31]
	s_mov_b32 s0, 0xc2680000
	s_mov_b32 s1, 0xc26c0000
	v_pk_add_f32 v[30:31], v[48:49], s[0:1] op_sel_hi:[0,1]
	v_cmp_le_f32_e32 vcc, 0, v31
	v_cmp_gt_f32_e64 s[8:9], s52, v31
	v_cmp_le_f32_e64 s[0:1], 0, v30
	v_cmp_gt_f32_e64 s[10:11], s52, v30
	s_and_b64 vcc, vcc, s[8:9]
	v_cndmask_b32_e32 v50, v160, v1, vcc
	s_and_b64 vcc, s[0:1], s[10:11]
	s_mov_b32 s0, 0x42600000
	s_mov_b32 s1, 0x42640000
	v_cndmask_b32_e32 v49, v160, v0, vcc
	v_pk_fma_f32 v[0:1], v[106:107], s[0:1], v[28:29]
	s_mov_b32 s0, 0xc2600000
	s_mov_b32 s1, 0xc2640000
	v_pk_add_f32 v[28:29], v[48:49], s[0:1] op_sel_hi:[0,1]
	v_cmp_le_f32_e32 vcc, 0, v29
	v_cmp_gt_f32_e64 s[8:9], s52, v29
	v_cmp_le_f32_e64 s[0:1], 0, v28
	v_cmp_gt_f32_e64 s[10:11], s52, v28
	s_and_b64 vcc, vcc, s[8:9]
	v_cndmask_b32_e32 v52, v160, v1, vcc
	s_and_b64 vcc, s[0:1], s[10:11]
	s_mov_b32 s0, 0x42480000
	s_mov_b32 s1, 0x424c0000
	v_cndmask_b32_e32 v51, v160, v0, vcc
	v_pk_fma_f32 v[0:1], v[106:107], s[0:1], v[26:27]
	s_mov_b32 s0, 0xc2480000
	s_mov_b32 s1, 0xc24c0000
	v_pk_add_f32 v[26:27], v[48:49], s[0:1] op_sel_hi:[0,1]
	v_cmp_le_f32_e32 vcc, 0, v27
	v_cmp_gt_f32_e64 s[8:9], s52, v27
	v_cmp_le_f32_e64 s[0:1], 0, v26
	v_cmp_gt_f32_e64 s[10:11], s52, v26
	s_and_b64 vcc, vcc, s[8:9]
	v_cndmask_b32_e32 v53, v160, v1, vcc
	s_and_b64 vcc, s[0:1], s[10:11]
	s_mov_b32 s0, 0xc2400000
	s_mov_b32 s1, 0xc2440000
	v_cndmask_b32_e32 v54, v160, v0, vcc
	v_pk_add_f32 v[0:1], v[48:49], s[0:1] op_sel_hi:[0,1]
	v_cmp_le_f32_e32 vcc, 0, v1
	v_cmp_gt_f32_e64 s[8:9], s52, v1
	v_pk_fma_f32 v[24:25], v[106:107], s[86:87], v[24:25]
	v_cmp_le_f32_e64 s[0:1], 0, v0
	v_cmp_gt_f32_e64 s[10:11], s52, v0
	s_and_b64 vcc, vcc, s[8:9]
	v_cndmask_b32_e32 v0, v160, v25, vcc
	s_and_b64 vcc, s[0:1], s[10:11]
	s_mov_b32 s0, 0x42280000
	s_mov_b32 s1, 0x422c0000
	v_cndmask_b32_e32 v1, v160, v24, vcc
; template <int KSTRIDE, bool WIN, int MASK, int MODE>
; DI void attend_tile(const u16* Ks, const u16* Vts, const bf16x8 (&qf)[4], f32x16 (&O)[2], float& m, float& l, int dbase,
;                     float slope2, bool lanesel, float invl, unsigned* imp_row, int mbase, int lr, int hh) {
;     ...
;   for (int kt = 0; kt < 2; ++kt)
; #pragma unroll
;     for (int e = 0; e < 16; ++e) {
;       const float Ke = (float)(KSTRIDE * (kt * 32 + (e & 3) + 8 * (e >> 2)));
;       float v = fmaf(slope2, Ke, s[kt][e]);
;       if (MASK == 1) {
;         const float fd = fd0 - Ke;
;         bool valid = fd >= 0.f;
;         if (WIN) valid = valid && (fd < 512.f);
;         valid = valid && lanesel;
;         v = valid ? v : -1e30f;
;       }
;       s[kt][e] = v;
;       mx = fmaxf(mx, v);
;     }
;   mx = (mx > -1e29f) ? mx - ct : -1e30f;
;   mx = fmaxf(mx, __shfl_xor(mx, 32));
;   if (MASK == 2) mx = lanesel ? mx : -1e30f;
	v_pk_fma_f32 v[24:25], v[106:107], s[0:1], v[22:23]
	s_mov_b32 s0, 0xc2280000
	s_mov_b32 s1, 0xc22c0000
	v_pk_add_f32 v[22:23], v[48:49], s[0:1] op_sel_hi:[0,1]
	v_cmp_le_f32_e32 vcc, 0, v23
	v_cmp_gt_f32_e64 s[8:9], s52, v23
	v_cmp_le_f32_e64 s[0:1], 0, v22
	v_cmp_gt_f32_e64 s[10:11], s52, v22
	s_and_b64 vcc, vcc, s[8:9]
	v_cndmask_b32_e32 v22, v160, v25, vcc
	s_and_b64 vcc, s[0:1], s[10:11]
	s_mov_b32 s0, 0x42200000
	s_mov_b32 s1, 0x42240000
	v_cndmask_b32_e32 v23, v160, v24, vcc
	v_pk_fma_f32 v[24:25], v[106:107], s[0:1], v[20:21]
	s_mov_b32 s0, 0xc2200000
	s_mov_b32 s1, 0xc2240000
	v_pk_add_f32 v[20:21], v[48:49], s[0:1] op_sel_hi:[0,1]
	v_cmp_le_f32_e32 vcc, 0, v21
	v_cmp_gt_f32_e64 s[8:9], s52, v21
	v_cmp_le_f32_e64 s[0:1], 0, v20
	v_cmp_gt_f32_e64 s[10:11], s52, v20
	s_and_b64 vcc, vcc, s[8:9]
	v_cndmask_b32_e32 v20, v160, v25, vcc
	s_and_b64 vcc, s[0:1], s[10:11]
	s_mov_b32 s0, 0x42080000
	s_mov_b32 s1, 0x420c0000
	v_cndmask_b32_e32 v21, v160, v24, vcc
	v_pk_fma_f32 v[24:25], v[106:107], s[0:1], v[18:19]
	s_mov_b32 s0, 0xc2080000
	s_mov_b32 s1, 0xc20c0000
	v_pk_add_f32 v[18:19], v[48:49], s[0:1] op_sel_hi:[0,1]
	v_cmp_le_f32_e32 vcc, 0, v19
	v_cmp_gt_f32_e64 s[8:9], s52, v19
	v_cmp_le_f32_e64 s[0:1], 0, v18
	v_cmp_gt_f32_e64 s[10:11], s52, v18
	s_and_b64 vcc, vcc, s[8:9]
	v_cndmask_b32_e32 v18, v160, v25, vcc
	s_and_b64 vcc, s[0:1], s[10:11]
	s_mov_b32 s0, 0xc2000000
	s_mov_b32 s1, 0xc2040000
	v_cndmask_b32_e32 v19, v160, v24, vcc
	v_pk_fma_f32 v[24:25], v[106:107], s[38:39], v[16:17]
	v_pk_add_f32 v[16:17], v[48:49], s[0:1] op_sel_hi:[0,1]
	v_cmp_le_f32_e32 vcc, 0, v17
	v_cmp_gt_f32_e64 s[8:9], s52, v17
	v_cmp_le_f32_e64 s[0:1], 0, v16
	v_cmp_gt_f32_e64 s[10:11], s52, v16
	s_and_b64 vcc, vcc, s[8:9]
	v_cndmask_b32_e32 v16, v160, v25, vcc
	s_and_b64 vcc, s[0:1], s[10:11]
	s_mov_b32 s0, 0x41d00000
	s_mov_b32 s1, 0x41d80000
	v_cndmask_b32_e32 v17, v160, v24, vcc
	v_pk_fma_f32 v[24:25], v[106:107], s[0:1], v[14:15]
	s_mov_b32 s0, 0xc1d00000
	s_mov_b32 s1, 0xc1d80000
	v_pk_add_f32 v[14:15], v[48:49], s[0:1] op_sel_hi:[0,1]
	v_cmp_le_f32_e32 vcc, 0, v15
	v_cmp_gt_f32_e64 s[8:9], s52, v15
	v_cmp_le_f32_e64 s[0:1], 0, v14
	v_cmp_gt_f32_e64 s[10:11], s52, v14
	s_and_b64 vcc, vcc, s[8:9]
	v_cndmask_b32_e32 v14, v160, v25, vcc
	s_and_b64 vcc, s[0:1], s[10:11]
	s_mov_b32 s0, 0x41c00000
	s_mov_b32 s1, 0x41c80000
	v_cndmask_b32_e32 v15, v160, v24, vcc
	v_pk_fma_f32 v[24:25], v[106:107], s[0:1], v[12:13]
	s_mov_b32 s0, 0xc1c00000
	s_mov_b32 s1, 0xc1c80000
	v_pk_add_f32 v[12:13], v[48:49], s[0:1] op_sel_hi:[0,1]
	v_cmp_le_f32_e32 vcc, 0, v13
	v_cmp_gt_f32_e64 s[8:9], s52, v13
	v_cmp_le_f32_e64 s[0:1], 0, v12
	v_cmp_gt_f32_e64 s[10:11], s52, v12
	s_and_b64 vcc, vcc, s[8:9]
	v_cndmask_b32_e32 v12, v160, v25, vcc
	s_and_b64 vcc, s[0:1], s[10:11]
	s_mov_b32 s0, 0x41900000
	s_mov_b32 s1, 0x41980000
	v_cndmask_b32_e32 v13, v160, v24, vcc
	v_pk_fma_f32 v[24:25], v[106:107], s[0:1], v[10:11]
	s_mov_b32 s0, 0xc1900000
	s_mov_b32 s1, 0xc1980000
	v_pk_add_f32 v[10:11], v[48:49], s[0:1] op_sel_hi:[0,1]
	v_cmp_le_f32_e32 vcc, 0, v11
	v_cmp_gt_f32_e64 s[8:9], s52, v11
	v_cmp_le_f32_e64 s[0:1], 0, v10
	v_cmp_gt_f32_e64 s[10:11], s52, v10
	s_and_b64 vcc, vcc, s[8:9]
	v_cndmask_b32_e32 v10, v160, v25, vcc
	s_and_b64 vcc, s[0:1], s[10:11]
	s_mov_b32 s0, 0xc1800000
	s_mov_b32 s1, 0xc1880000
	v_cndmask_b32_e32 v11, v160, v24, vcc
	v_pk_add_f32 v[24:25], v[48:49], s[0:1] op_sel_hi:[0,1]
	v_cmp_le_f32_e32 vcc, 0, v25
	v_cmp_gt_f32_e64 s[8:9], s52, v25
	v_cmp_le_f32_e64 s[0:1], 0, v24
	v_cmp_gt_f32_e64 s[10:11], s52, v24
	s_and_b64 vcc, vcc, s[8:9]
	v_cndmask_b32_e32 v24, v160, v9, vcc
	s_and_b64 vcc, s[0:1], s[10:11]
	s_mov_b32 s0, 0xc1200000
	s_mov_b32 s1, 0xc1300000
	v_cndmask_b32_e32 v25, v160, v8, vcc
	v_pk_add_f32 v[8:9], v[48:49], s[0:1] op_sel_hi:[0,1]
	v_cmp_le_f32_e32 vcc, 0, v9
	v_cmp_gt_f32_e64 s[8:9], s52, v9
	v_cmp_le_f32_e64 s[0:1], 0, v8
	v_cmp_gt_f32_e64 s[10:11], s52, v8
	s_and_b64 vcc, vcc, s[8:9]
	v_cndmask_b32_e32 v26, v160, v7, vcc
	s_and_b64 vcc, s[0:1], s[10:11]
	s_mov_b32 s0, 0xc1000000
	s_mov_b32 s1, 0xc1100000
	v_cndmask_b32_e32 v27, v160, v6, vcc
	v_pk_fma_f32 v[6:7], v[106:107], s[70:71], v[4:5]
	v_pk_add_f32 v[4:5], v[48:49], s[0:1] op_sel_hi:[0,1]
	v_cmp_le_f32_e32 vcc, 0, v5
	v_cmp_gt_f32_e64 s[8:9], s52, v5
	v_cmp_le_f32_e64 s[0:1], 0, v4
	v_cmp_gt_f32_e64 s[10:11], s52, v4
	s_and_b64 vcc, vcc, s[8:9]
	v_cndmask_b32_e32 v4, v160, v7, vcc
	s_and_b64 vcc, s[0:1], s[10:11]
	s_mov_b32 s0, -2.0
	s_mov_b32 s1, 0xc0400000
	v_cndmask_b32_e32 v5, v160, v6, vcc
	v_pk_fma_f32 v[6:7], v[106:107], s[68:69], v[2:3]
	v_pk_add_f32 v[2:3], v[48:49], s[0:1] op_sel_hi:[0,1]
	v_cmp_le_f32_e32 vcc, 0, v3
	v_cmp_gt_f32_e64 s[8:9], s52, v3
	v_cmp_le_f32_e64 s[0:1], 0, v2
	v_cmp_gt_f32_e64 s[10:11], s52, v2
	s_and_b64 vcc, vcc, s[8:9]
	v_cndmask_b32_e32 v2, v160, v7, vcc
	s_and_b64 vcc, s[0:1], s[10:11]
	v_cndmask_b32_e32 v3, v160, v6, vcc
	v_max3_f32 v6, v57, v3, v2
	v_max3_f32 v6, v6, v5, v4
	v_max3_f32 v6, v6, v27, v26
	v_max3_f32 v6, v6, v25, v24
	v_max3_f32 v6, v6, v11, v10
	v_max3_f32 v6, v6, v13, v12
	v_max3_f32 v6, v6, v15, v14
	v_max3_f32 v6, v6, v17, v16
	v_max3_f32 v6, v6, v19, v18
	v_max3_f32 v6, v6, v21, v20
	v_max3_f32 v6, v6, v23, v22
	v_max3_f32 v6, v6, v1, v0
	v_max3_f32 v6, v6, v54, v53
	v_max3_f32 v6, v6, v51, v52
	v_max3_f32 v6, v6, v49, v50
	v_fma_f32 v7, -v106, v48, v6
	v_cmp_lt_f32_e32 vcc, s76, v6
	s_nop 1
	v_cndmask_b32_e32 v28, v160, v7, vcc
	v_mov_b32_e32 v29, v28
	s_nop 1
	v_permlane32_swap_b32_e32 v29, v28
	s_nop 1
	v_cmp_lt_f32_e32 vcc, s76, v55
	s_nop 0
	s_waitcnt lgkmcnt(1)
; DI float fexp2(float x) { return __builtin_amdgcn_exp2f(x); }
; template <int KSTRIDE, bool WIN, int MASK, int MODE>
; DI void attend_tile(const u16* Ks, const u16* Vts, const bf16x8 (&qf)[4], f32x16 (&O)[2], float& m, float& l, int dbase,
;                     float slope2, bool lanesel, float invl, unsigned* imp_row, int mbase, int lr, int hh) {
;     ...
;   float rs = 0.f;
; #pragma unroll
;   for (int kt = 0; kt < 2; ++kt)
; #pragma unroll
;     for (int e = 0; e < 16; ++e) {
;       float v = s[kt][e];
;       float pv;
;       if (MASK == 1) pv = (v > -1e29f) ? fexp2(v - shift) : 0.f;
;       else pv = fexp2(v - shift);
;       if (MODE == 2) pv *= invl;
;       s[kt][e] = pv;
;       rs += pv;
;     }
;   if (MODE != 2) l = l * alpha + rs;
;   if (MODE == 1) return;
;   if (MODE == 0) {
; #pragma unroll
;     for (int e = 0; e < 16; ++e) { O[0][e] *= alpha; O[1][e] *= alpha; }
	v_max3_f32 v145, v143, v28, v29
	v_fma_f32 v48, v106, v48, v145
	v_sub_f32_e32 v29, v55, v48
	v_exp_f32_e32 v29, v29
	v_sub_f32_e32 v30, v56, v48
	v_exp_f32_e32 v30, v30
	v_sub_f32_e32 v31, v3, v48
	v_cndmask_b32_e32 v55, 0, v29, vcc
	v_cmp_lt_f32_e32 vcc, s76, v56
	v_exp_f32_e32 v31, v31
	v_add_f32_e32 v29, 0, v55
	v_cndmask_b32_e32 v56, 0, v30, vcc
	v_sub_f32_e32 v30, v2, v48
	v_exp_f32_e32 v30, v30
	v_cmp_lt_f32_e32 vcc, s76, v2
	v_add_f32_e32 v29, v56, v29
	v_sub_f32_e32 v28, v143, v145
	v_cndmask_b32_e32 v57, 0, v30, vcc
	v_cmp_lt_f32_e32 vcc, s76, v3
	v_sub_f32_e32 v3, v4, v48
	v_exp_f32_e32 v3, v3
	v_cndmask_b32_e32 v58, 0, v31, vcc
	v_add_f32_e32 v2, v58, v29
	v_sub_f32_e32 v29, v5, v48
	v_cmp_lt_f32_e32 vcc, s76, v4
	v_exp_f32_e32 v29, v29
	v_sub_f32_e32 v4, v27, v48
	v_cndmask_b32_e32 v59, 0, v3, vcc
	v_sub_f32_e32 v3, v26, v48
	v_exp_f32_e32 v3, v3
	v_exp_f32_e32 v4, v4
	v_cmp_lt_f32_e32 vcc, s76, v5
	v_add_f32_e32 v2, v57, v2
	v_exp_f32_e32 v148, v28
	v_cndmask_b32_e32 v60, 0, v29, vcc
	v_cmp_lt_f32_e32 vcc, s76, v26
	v_add_f32_e32 v2, v60, v2
	v_add_f32_e32 v2, v59, v2
	v_cndmask_b32_e32 v61, 0, v3, vcc
	v_cmp_lt_f32_e32 vcc, s76, v27
	v_sub_f32_e32 v3, v24, v48
	v_exp_f32_e32 v3, v3
	v_cndmask_b32_e32 v62, 0, v4, vcc
	v_sub_f32_e32 v4, v25, v48
	v_exp_f32_e32 v4, v4
	v_cmp_lt_f32_e32 vcc, s76, v24
	v_add_f32_e32 v2, v62, v2
	v_add_f32_e32 v2, v61, v2
	v_cndmask_b32_e32 v143, 0, v3, vcc
	v_cmp_lt_f32_e32 vcc, s76, v25
	v_sub_f32_e32 v3, v10, v48
	v_exp_f32_e32 v3, v3
	v_cndmask_b32_e32 v146, 0, v4, vcc
	v_sub_f32_e32 v4, v11, v48
	v_exp_f32_e32 v4, v4
	v_cmp_lt_f32_e32 vcc, s76, v10
	v_add_f32_e32 v2, v146, v2
	v_add_f32_e32 v2, v143, v2
	v_cndmask_b32_e32 v147, 0, v3, vcc
	v_cmp_lt_f32_e32 vcc, s76, v11
	v_sub_f32_e32 v3, v12, v48
	v_exp_f32_e32 v3, v3
	v_cndmask_b32_e32 v149, 0, v4, vcc
	v_sub_f32_e32 v4, v13, v48
	v_exp_f32_e32 v4, v4
	v_cmp_lt_f32_e32 vcc, s76, v12
	v_add_f32_e32 v2, v149, v2
	v_add_f32_e32 v2, v147, v2
	v_cndmask_b32_e32 v150, 0, v3, vcc
	v_cmp_lt_f32_e32 vcc, s76, v13
	v_sub_f32_e32 v3, v14, v48
	v_exp_f32_e32 v3, v3
	v_cndmask_b32_e32 v151, 0, v4, vcc
	v_sub_f32_e32 v4, v15, v48
	v_exp_f32_e32 v4, v4
	v_cmp_lt_f32_e32 vcc, s76, v14
	v_add_f32_e32 v2, v151, v2
	v_add_f32_e32 v2, v150, v2
	v_cndmask_b32_e32 v152, 0, v3, vcc
	v_cmp_lt_f32_e32 vcc, s76, v15
	v_sub_f32_e32 v3, v16, v48
	v_exp_f32_e32 v3, v3
	v_cndmask_b32_e32 v153, 0, v4, vcc
	v_sub_f32_e32 v4, v17, v48
	v_exp_f32_e32 v4, v4
	v_cmp_lt_f32_e32 vcc, s76, v16
	v_add_f32_e32 v2, v153, v2
	v_add_f32_e32 v2, v152, v2
	v_cndmask_b32_e32 v164, 0, v3, vcc
	v_cmp_lt_f32_e32 vcc, s76, v17
	v_sub_f32_e32 v3, v18, v48
	v_exp_f32_e32 v3, v3
	v_cndmask_b32_e32 v165, 0, v4, vcc
	v_sub_f32_e32 v4, v19, v48
	v_exp_f32_e32 v4, v4
	v_cmp_lt_f32_e32 vcc, s76, v18
	v_add_f32_e32 v2, v165, v2
	v_add_f32_e32 v2, v164, v2
	v_cndmask_b32_e32 v166, 0, v3, vcc
	v_cmp_lt_f32_e32 vcc, s76, v19
	v_sub_f32_e32 v3, v20, v48
	v_exp_f32_e32 v3, v3
	v_cndmask_b32_e32 v167, 0, v4, vcc
	v_sub_f32_e32 v4, v21, v48
	v_exp_f32_e32 v4, v4
	v_cmp_lt_f32_e32 vcc, s76, v20
	v_add_f32_e32 v2, v167, v2
	v_cvt_pk_bf16_f32 v57, v58, v57
	v_cndmask_b32_e32 v168, 0, v3, vcc
	v_cmp_lt_f32_e32 vcc, s76, v21
	v_sub_f32_e32 v3, v22, v48
	v_exp_f32_e32 v3, v3
	v_cndmask_b32_e32 v169, 0, v4, vcc
	v_sub_f32_e32 v4, v23, v48
	v_exp_f32_e32 v4, v4
	v_cmp_lt_f32_e32 vcc, s76, v22
	v_cvt_pk_bf16_f32 v58, v60, v59
	v_cvt_pk_bf16_f32 v59, v62, v61
	v_cndmask_b32_e32 v170, 0, v3, vcc
	v_cmp_lt_f32_e32 vcc, s76, v23
	v_sub_f32_e32 v3, v0, v48
	v_exp_f32_e32 v3, v3
	v_cndmask_b32_e32 v171, 0, v4, vcc
	v_sub_f32_e32 v4, v1, v48
	s_nop 0
	v_add_f32_e32 v2, v166, v2
	v_exp_f32_e32 v4, v4
	v_pk_mul_f32 v[16:17], v[108:109], v[148:149] op_sel_hi:[1,0]
	v_pk_mul_f32 v[18:19], v[110:111], v[148:149] op_sel_hi:[1,0]
	v_pk_mul_f32 v[20:21], v[112:113], v[148:149] op_sel_hi:[1,0]
	v_pk_mul_f32 v[22:23], v[114:115], v[148:149] op_sel_hi:[1,0]
	v_pk_mul_f32 v[24:25], v[118:119], v[148:149] op_sel_hi:[1,0]
	v_pk_mul_f32 v[26:27], v[120:121], v[148:149] op_sel_hi:[1,0]
	v_pk_mul_f32 v[28:29], v[122:123], v[148:149] op_sel_hi:[1,0]
	v_pk_mul_f32 v[30:31], v[124:125], v[148:149] op_sel_hi:[1,0]
	v_cvt_pk_bf16_f32 v56, v55, v56
	v_add_f32_e32 v2, v169, v2
	v_add_f32_e32 v2, v168, v2
	s_waitcnt lgkmcnt(1)
; #define MFMA32(a, b, c) __builtin_amdgcn_mfma_f32_32x32x16_bf16((a), (b), (c), 0, 0, 0)
; template <int KSTRIDE, bool WIN, int MASK, int MODE>
; DI void attend_tile(const u16* Ks, const u16* Vts, const bf16x8 (&qf)[4], f32x16 (&O)[2], float& m, float& l, int dbase,
;                     float slope2, bool lanesel, float invl, unsigned* imp_row, int mbase, int lr, int hh) {
;     ...
;   if (MODE != 2) l = l * alpha + rs;
;   if (MODE == 1) return;
;   if (MODE == 0) {
; #pragma unroll
;     for (int e = 0; e < 16; ++e) { O[0][e] *= alpha; O[1][e] *= alpha; }
;   }
;   if (MODE == 2) {
; #pragma unroll
;     for (int kt = 0; kt < 2; ++kt)
; #pragma unroll
;       for (int q4 = 0; q4 < 4; ++q4) {
;         float qsum = s[kt][q4 * 4] + s[kt][q4 * 4 + 1] + s[kt][q4 * 4 + 2] + s[kt][q4 * 4 + 3];
;         float last = s[kt][q4 * 4 + 3];
;         int mi = mbase + kt * 8 + 2 * q4 + hh;
;         atomicAdd(imp_row + mi, (unsigned)(qsum * 1048576.f + 0.5f));
;         if (mi + 1 < 64) atomicAdd(imp_row + mi + 1, (unsigned)(last * 1048576.f + 0.5f));
;       }
;   }
; #pragma unroll
;   for (int kt = 0; kt < 2; ++kt)
; #pragma unroll
;     for (int sx = 0; sx < 2; ++sx) {
;       unsigned pk[4];
; #pragma unroll
;       for (int q = 0; q < 4; ++q) pk[q] = pack2(s[kt][8 * sx + 2 * q], s[kt][8 * sx + 2 * q + 1]);
;       bf16x8 pb;
;       {
;         u32x4 t4 = {pk[0], pk[1], pk[2], pk[3]};
;         pb = __builtin_bit_cast(bf16x8, t4);
;       }
; #pragma unroll
;       for (int dt = 0; dt < 2; ++dt) {
;         bf16x8 a = *(const bf16x8*)(Vts + (dt * 32 + lr) * 72 + kt * 32 + 16 * sx + 8 * hh);
;         O[dt] = MFMA32(a, pb, O[dt]);
;       }
;     }
	v_mfma_f32_32x32x16_bf16 v[16:31], v[200:203], v[56:59], v[16:31]
	v_cmp_lt_f32_e32 vcc, s76, v0
	v_add_f32_e32 v2, v171, v2
	v_add_f32_e32 v2, v170, v2
	v_cndmask_b32_e32 v172, 0, v3, vcc
	v_cmp_lt_f32_e32 vcc, s76, v1
	s_nop 0
	s_nop 0
	v_cndmask_b32_e32 v173, 0, v4, vcc
	v_add_f32_e32 v0, v173, v2
	v_add_f32_e32 v174, v172, v0
	v_sub_f32_e32 v0, v54, v48
	v_exp_f32_e32 v175, v0
	v_pk_mul_f32 v[0:1], v[132:133], v[148:149] op_sel_hi:[1,0]
	v_pk_mul_f32 v[2:3], v[134:135], v[148:149] op_sel_hi:[1,0]
	v_pk_mul_f32 v[4:5], v[138:139], v[148:149] op_sel_hi:[1,0]
	v_pk_mul_f32 v[6:7], v[126:127], v[148:149] op_sel_hi:[1,0]
	v_pk_mul_f32 v[8:9], v[128:129], v[148:149] op_sel_hi:[1,0]
	v_pk_mul_f32 v[10:11], v[130:131], v[148:149] op_sel_hi:[1,0]
	v_pk_mul_f32 v[12:13], v[136:137], v[148:149] op_sel_hi:[1,0]
	v_pk_mul_f32 v[14:15], v[140:141], v[148:149] op_sel_hi:[1,0]
	v_sub_f32_e32 v55, v53, v48
	v_exp_f32_e32 v55, v55
	s_waitcnt lgkmcnt(2)
	v_mfma_f32_32x32x16_bf16 v[0:15], v[204:207], v[56:59], v[0:15]
	v_cvt_pk_bf16_f32 v56, v146, v143
	v_cvt_pk_bf16_f32 v57, v149, v147
	v_cvt_pk_bf16_f32 v58, v151, v150
	v_cvt_pk_bf16_f32 v59, v153, v152
	s_nop 0
	s_nop 0
	v_cmp_lt_f32_e32 vcc, s76, v53
	s_waitcnt lgkmcnt(3)
	v_mfma_f32_32x32x16_bf16 v[16:31], v[214:217], v[56:59], v[16:31]
	s_nop 0
	v_cndmask_b32_e32 v112, 0, v55, vcc
	v_cmp_lt_f32_e32 vcc, s76, v54
	v_sub_f32_e32 v54, v52, v48
	v_exp_f32_e32 v54, v54
	v_cndmask_b32_e32 v113, 0, v175, vcc
	v_sub_f32_e32 v53, v51, v48
	s_waitcnt lgkmcnt(0)
	v_mfma_f32_32x32x16_bf16 v[0:15], v[230:233], v[56:59], v[0:15]
	v_cmp_lt_f32_e32 vcc, s76, v52
	v_exp_f32_e32 v56, v53
	v_cvt_pk_bf16_f32 v52, v165, v164
	v_cndmask_b32_e32 v57, 0, v54, vcc
	v_cvt_pk_bf16_f32 v53, v167, v166
	v_cvt_pk_bf16_f32 v54, v169, v168
	v_cvt_pk_bf16_f32 v55, v171, v170
	v_cmp_lt_f32_e32 vcc, s76, v51
	v_sub_f32_e32 v51, v50, v48
	v_mfma_f32_32x32x16_bf16 v[16:31], v[222:225], v[52:55], v[16:31]
	v_exp_f32_e32 v51, v51
	v_sub_f32_e32 v48, v49, v48
	v_exp_f32_e32 v48, v48
	v_cndmask_b32_e32 v56, 0, v56, vcc
	v_cmp_lt_f32_e32 vcc, s76, v50
	v_cvt_pk_bf16_f32 v50, v56, v57
	v_add_f32_e32 v60, v113, v174
	v_mfma_f32_32x32x16_bf16 v[0:15], v[226:229], v[52:55], v[0:15]
	s_nop 0
	v_cndmask_b32_e32 v58, 0, v51, vcc
	v_cmp_lt_f32_e32 vcc, s76, v49
	v_cvt_pk_bf16_f32 v49, v113, v112
	v_add_f32_e32 v60, v112, v60
	v_cndmask_b32_e32 v59, 0, v48, vcc
	v_cvt_pk_bf16_f32 v48, v173, v172
	v_cvt_pk_bf16_f32 v51, v59, v58
	v_add_f32_e32 v56, v56, v60
	v_add_f32_e32 v56, v57, v56
	v_mfma_f32_32x32x16_bf16 v[16:31], v[218:221], v[48:51], v[16:31]
	v_add_f32_e32 v56, v59, v56
	v_add_f32_e32 v146, v58, v56
	v_fmac_f32_e32 v146, v142, v148
	s_waitcnt lgkmcnt(0)
	v_mfma_f32_32x32x16_bf16 v[0:15], v[234:237], v[48:51], v[0:15]
	s_nop 7
	s_nop 3

; #define MFMA32(a, b, c) __builtin_amdgcn_mfma_f32_32x32x16_bf16((a), (b), (c), 0, 0, 0)
; template <int KSTRIDE, bool WIN, int MASK, int MODE>
; DI void attend_tile(const u16* Ks, const u16* Vts, const bf16x8 (&qf)[4], f32x16 (&O)[2], float& m, float& l, int dbase,
;                     float slope2, bool lanesel, float invl, unsigned* imp_row, int mbase, int lr, int hh) {
;     ...
;   for (int kt = 0; kt < 2; ++kt) {
; #pragma unroll
;     for (int e = 0; e < 16; ++e) s[kt][e] = 0.f;
; #pragma unroll
;     for (int ks = 0; ks < 4; ++ks) {
;       bf16x8 a = *(const bf16x8*)(Ks + (kt * 32 + lr) * 72 + ks * 16 + hh * 8);
;       s[kt] = MFMA32(a, qf[ks], s[kt]);
;     }
;   }
;   const float fd0 = (float)(dbase - KSTRIDE * 4 * hh);
;   const float ct = slope2 * fd0;
;   float mx = -1e30f;
; #pragma unroll
;   for (int kt = 0; kt < 2; ++kt)
; #pragma unroll
;     for (int e = 0; e < 16; ++e) {
;       const float Ke = (float)(KSTRIDE * (kt * 32 + (e & 3) + 8 * (e >> 2)));
;       float v = fmaf(slope2, Ke, s[kt][e]);
;       if (MASK == 1) {
;         const float fd = fd0 - Ke;
;         bool valid = fd >= 0.f;
;         if (WIN) valid = valid && (fd < 512.f);
;         valid = valid && lanesel;
;         v = valid ? v : -1e30f;
;       }
;       s[kt][e] = v;
;       mx = fmaxf(mx, v);
;     }
;   mx = (mx > -1e29f) ? mx - ct : -1e30f;
;   mx = fmaxf(mx, __shfl_xor(mx, 32));
;   if (MASK == 2) mx = lanesel ? mx : -1e30f;
; DI void attn_item(const Params& p, int item, char* smem) {
;     ...
;       bool ls = (j < 32) ? ((mylo >> j) & 1u) : ((myhi >> (j - 32)) & 1u);
;       if (j < qb) attend_tile<1, false, 2, 0>(Ks, Vts, qf, O, m, l, t - 64 * j, slope2, ls, 0.f, nullptr, 0, lr, hh);
;       else attend_tile<1, false, 1, 0>(Ks, Vts, qf, O, m, l, t - 64 * j, slope2, ls, 0.f, nullptr, 0, lr, hh);
.LBB0_642:
	v_add3_u32 v165, s81, v161, v162
	s_waitcnt lgkmcnt(8)
	ds_read_b128 v[48:51], v165
	s_waitcnt lgkmcnt(8)
	ds_read_b128 v[44:47], v165 offset:32
	s_waitcnt lgkmcnt(8)
	ds_read_b128 v[32:35], v165 offset:64
	s_waitcnt lgkmcnt(8)
	ds_read_b128 v[36:39], v165 offset:96
	s_waitcnt lgkmcnt(8)
	ds_read_b128 v[40:43], v165 offset:4608
	v_sub_co_u32_e64 v1, vcc, s80, 32
	v_lshrrev_b32_e32 v0, s80, v62
	v_lshrrev_b32_e32 v1, v1, v63
	v_cndmask_b32_e32 v0, v1, v0, vcc
	v_and_b32_e32 v0, 1, v0
	v_cmp_eq_u32_e64 s[0:1], 1, v0
	s_cmp_ge_u32 s80, s86
	s_mov_b64 vcc, -1
	s_cbranch_scc0 .LBB0_644
	s_waitcnt lgkmcnt(4)
	v_mfma_f32_32x32x16_bf16 v[16:31], v[48:51], v[64:67], 0
	ds_read_b128 v[52:55], v165 offset:4640
	ds_read_b128 v[170:173], v165 offset:4672
	s_lshl_b32 s81, s80, 6
	s_waitcnt lgkmcnt(2)
	v_mfma_f32_32x32x16_bf16 v[0:15], v[40:43], v[64:67], 0
	v_mfma_f32_32x32x16_bf16 v[16:31], v[44:47], v[68:71], v[16:31]
	s_waitcnt lgkmcnt(1)
	v_mfma_f32_32x32x16_bf16 v[0:15], v[52:55], v[68:71], v[0:15]
	ds_read_b128 v[52:55], v165 offset:4704
	v_mfma_f32_32x32x16_bf16 v[16:31], v[32:35], v[72:75], v[16:31]
	s_waitcnt lgkmcnt(1)
	v_mfma_f32_32x32x16_bf16 v[0:15], v[170:173], v[72:75], v[0:15]
	v_mfma_f32_32x32x16_bf16 v[16:31], v[36:39], v[76:79], v[16:31]
	s_waitcnt lgkmcnt(0)
	v_mfma_f32_32x32x16_bf16 v[0:15], v[52:55], v[76:79], v[0:15]
	ds_read_b128 v[200:203], v165 offset:9216
	ds_read_b128 v[204:207], v165 offset:13824
	ds_read_b128 v[214:217], v165 offset:9248
	ds_read_b128 v[218:221], v165 offset:13856
	ds_read_b128 v[222:225], v165 offset:9280
	ds_read_b128 v[226:229], v165 offset:13888
	ds_read_b128 v[230:233], v165 offset:9312
	ds_read_b128 v[234:237], v165 offset:13920
	v_subrev_u32_e32 v52, s81, v57
	v_cmp_lt_i32_e32 vcc, -1, v52
	s_nop 7
	v_fma_f32 v16, 0, v106, v16
	s_and_b64 vcc, vcc, s[0:1]
	v_cndmask_b32_e32 v16, v160, v16, vcc
	v_cmp_lt_i32_e32 vcc, 0, v52
	v_add_f32_e32 v17, v106, v17
	s_and_b64 vcc, vcc, s[0:1]
	v_cndmask_b32_e32 v17, v160, v17, vcc
	v_cmp_lt_i32_e32 vcc, 1, v52
	v_fma_f32 v18, 2.0, v106, v18
	s_and_b64 vcc, vcc, s[0:1]
	v_cndmask_b32_e32 v18, v160, v18, vcc
	v_cmp_lt_i32_e32 vcc, 2, v52
	v_fmamk_f32 v19, v106, 0x40400000, v19
	s_and_b64 vcc, vcc, s[0:1]
	v_cndmask_b32_e32 v19, v160, v19, vcc
	v_cmp_lt_i32_e32 vcc, 7, v52
	v_fmamk_f32 v20, v106, 0x41000000, v20
	s_and_b64 vcc, vcc, s[0:1]
	v_cndmask_b32_e32 v20, v160, v20, vcc
	v_cmp_lt_i32_e32 vcc, 8, v52
	v_fmamk_f32 v21, v106, 0x41100000, v21
	s_and_b64 vcc, vcc, s[0:1]
	v_cndmask_b32_e32 v21, v160, v21, vcc
	v_cmp_lt_i32_e32 vcc, 9, v52
	v_fmamk_f32 v22, v106, 0x41200000, v22
	s_and_b64 vcc, vcc, s[0:1]
	v_cndmask_b32_e32 v22, v160, v22, vcc
	v_cmp_lt_i32_e32 vcc, 10, v52
	v_fmamk_f32 v23, v106, 0x41300000, v23
	s_and_b64 vcc, vcc, s[0:1]
	v_cndmask_b32_e32 v23, v160, v23, vcc
	v_cmp_lt_i32_e32 vcc, 15, v52
	v_fmamk_f32 v24, v106, 0x41800000, v24
	s_and_b64 vcc, vcc, s[0:1]
	v_cndmask_b32_e32 v24, v160, v24, vcc
	v_cmp_lt_i32_e32 vcc, 16, v52
	v_fmamk_f32 v25, v106, 0x41880000, v25
	s_and_b64 vcc, vcc, s[0:1]
	v_cndmask_b32_e32 v25, v160, v25, vcc
	v_cmp_lt_i32_e32 vcc, 17, v52
	v_fmamk_f32 v26, v106, 0x41900000, v26
	s_and_b64 vcc, vcc, s[0:1]
	v_cndmask_b32_e32 v26, v160, v26, vcc
	v_cmp_lt_i32_e32 vcc, 18, v52
	v_fmamk_f32 v27, v106, 0x41980000, v27
	s_and_b64 vcc, vcc, s[0:1]
	v_cndmask_b32_e32 v27, v160, v27, vcc
	v_cmp_lt_i32_e32 vcc, 23, v52
	v_fmamk_f32 v28, v106, 0x41c00000, v28
	s_and_b64 vcc, vcc, s[0:1]
	v_cndmask_b32_e32 v28, v160, v28, vcc
	v_cmp_lt_i32_e32 vcc, 24, v52
	v_fmamk_f32 v29, v106, 0x41c80000, v29
	s_and_b64 vcc, vcc, s[0:1]
	v_cndmask_b32_e32 v29, v160, v29, vcc
	v_cmp_lt_i32_e32 vcc, 25, v52
	v_fmamk_f32 v30, v106, 0x41d00000, v30
	s_and_b64 vcc, vcc, s[0:1]
	v_cndmask_b32_e32 v30, v160, v30, vcc
	v_cmp_lt_i32_e32 vcc, 26, v52
	v_fmac_f32_e32 v31, 0x41d80000, v106
	s_and_b64 vcc, vcc, s[0:1]
	v_cndmask_b32_e32 v31, v160, v31, vcc
	v_cmp_lt_i32_e32 vcc, 31, v52
	v_fmamk_f32 v0, v106, 0x42000000, v0
	s_and_b64 vcc, vcc, s[0:1]
	v_cndmask_b32_e32 v0, v160, v0, vcc
	v_cmp_lt_i32_e32 vcc, 32, v52
	v_fmamk_f32 v1, v106, 0x42040000, v1
	s_and_b64 vcc, vcc, s[0:1]
	v_cndmask_b32_e32 v1, v160, v1, vcc
	v_cmp_lt_i32_e32 vcc, 33, v52
	v_fmamk_f32 v2, v106, 0x42080000, v2
	s_and_b64 vcc, vcc, s[0:1]
	v_cndmask_b32_e32 v2, v160, v2, vcc
	v_cmp_lt_i32_e32 vcc, 34, v52
	v_fmamk_f32 v3, v106, 0x420c0000, v3
	s_and_b64 vcc, vcc, s[0:1]
	v_cndmask_b32_e32 v3, v160, v3, vcc
	v_cmp_lt_i32_e32 vcc, 39, v52
	v_fmamk_f32 v4, v106, 0x42200000, v4
	s_and_b64 vcc, vcc, s[0:1]
	v_cndmask_b32_e32 v4, v160, v4, vcc
	v_cmp_lt_i32_e32 vcc, 40, v52
	v_fmamk_f32 v5, v106, 0x42240000, v5
	s_and_b64 vcc, vcc, s[0:1]
	v_cndmask_b32_e32 v5, v160, v5, vcc
	v_cmp_lt_i32_e32 vcc, 41, v52
	v_fmamk_f32 v6, v106, 0x42280000, v6
	s_and_b64 vcc, vcc, s[0:1]
	v_cndmask_b32_e32 v6, v160, v6, vcc
	v_cmp_lt_i32_e32 vcc, 42, v52
	v_fmamk_f32 v7, v106, 0x422c0000, v7
	s_and_b64 vcc, vcc, s[0:1]
	v_cndmask_b32_e32 v7, v160, v7, vcc
	v_cmp_lt_i32_e32 vcc, 47, v52
	v_fmamk_f32 v8, v106, 0x42400000, v8
	s_and_b64 vcc, vcc, s[0:1]
	v_max3_f32 v54, v16, s95, v17
	v_cndmask_b32_e32 v8, v160, v8, vcc
	v_cmp_lt_i32_e32 vcc, 48, v52
	v_max3_f32 v54, v54, v18, v19
	v_fmamk_f32 v9, v106, 0x42440000, v9
	s_and_b64 vcc, vcc, s[0:1]
	v_max3_f32 v54, v54, v20, v21
	v_cndmask_b32_e32 v9, v160, v9, vcc
	v_cmp_lt_i32_e32 vcc, 49, v52
	v_max3_f32 v54, v54, v22, v23
	v_fmamk_f32 v10, v106, 0x42480000, v10
	s_and_b64 vcc, vcc, s[0:1]
	v_max3_f32 v54, v54, v24, v25
	v_cndmask_b32_e32 v10, v160, v10, vcc
	v_cmp_lt_i32_e32 vcc, 50, v52
	v_max3_f32 v54, v54, v26, v27
	v_fmamk_f32 v11, v106, 0x424c0000, v11
	s_and_b64 vcc, vcc, s[0:1]
	v_max3_f32 v54, v54, v28, v29
	v_cndmask_b32_e32 v11, v160, v11, vcc
	v_cmp_lt_i32_e32 vcc, 55, v52
	v_max3_f32 v54, v54, v30, v31
	v_fmamk_f32 v12, v106, 0x42600000, v12
	s_and_b64 vcc, vcc, s[0:1]
	v_max3_f32 v54, v54, v0, v1
	v_cndmask_b32_e32 v12, v160, v12, vcc
	v_cmp_lt_i32_e32 vcc, 56, v52
	v_max3_f32 v54, v54, v2, v3
	v_fmamk_f32 v13, v106, 0x42640000, v13
	s_and_b64 vcc, vcc, s[0:1]
	v_max3_f32 v54, v54, v4, v5
	v_cndmask_b32_e32 v13, v160, v13, vcc
	v_cmp_lt_i32_e32 vcc, 57, v52
	v_max3_f32 v54, v54, v6, v7
	v_fmamk_f32 v14, v106, 0x42680000, v14
	s_and_b64 vcc, vcc, s[0:1]
	v_cvt_f32_i32_e32 v53, v52
	v_max3_f32 v54, v54, v8, v9
	v_cndmask_b32_e32 v14, v160, v14, vcc
	v_cmp_lt_i32_e32 vcc, 58, v52
	v_max3_f32 v54, v54, v10, v11
	v_fmac_f32_e32 v15, 0x426c0000, v106
	s_and_b64 vcc, vcc, s[0:1]
	v_max3_f32 v54, v54, v12, v13
	v_cndmask_b32_e32 v15, v160, v15, vcc
	v_max3_f32 v52, v54, v14, v15
	v_cmp_lt_f32_e32 vcc, s76, v52
	v_fma_f32 v52, -v106, v53, v52
	s_nop 0
	v_cndmask_b32_e32 v52, v160, v52, vcc
	v_mov_b32_e32 v54, v52
	s_nop 1
	v_permlane32_swap_b32_e32 v54, v52
	s_nop 1
	v_cmp_lt_f32_e32 vcc, s76, v16
	s_waitcnt lgkmcnt(0)
; DI float fexp2(float x) { return __builtin_amdgcn_exp2f(x); }
; template <int KSTRIDE, bool WIN, int MASK, int MODE>
; DI void attend_tile(const u16* Ks, const u16* Vts, const bf16x8 (&qf)[4], f32x16 (&O)[2], float& m, float& l, int dbase,
;                     float slope2, bool lanesel, float invl, unsigned* imp_row, int mbase, int lr, int hh) {
;     ...
;   float shift = mnew + ct;
;   if (MASK == 2) shift = lanesel ? shift : 1e30f;
;   float rs = 0.f;
; #pragma unroll
;   for (int kt = 0; kt < 2; ++kt)
; #pragma unroll
;     for (int e = 0; e < 16; ++e) {
;       float v = s[kt][e];
;       float pv;
;       if (MASK == 1) pv = (v > -1e29f) ? fexp2(v - shift) : 0.f;
;       else pv = fexp2(v - shift);
;       if (MODE == 2) pv *= invl;
;       s[kt][e] = pv;
;       rs += pv;
;     }
;   if (MODE != 2) l = l * alpha + rs;
;   if (MODE == 1) return;
;   if (MODE == 0) {
; #pragma unroll
;     for (int e = 0; e < 16; ++e) { O[0][e] *= alpha; O[1][e] *= alpha; }
;     ...
;       for (int q = 0; q < 4; ++q) pk[q] = pack2(s[kt][8 * sx + 2 * q], s[kt][8 * sx + 2 * q + 1]);
	v_max3_f32 v166, v169, v52, v54
	v_fma_f32 v53, v106, v53, v166
	v_sub_f32_e32 v16, v16, v53
	v_exp_f32_e32 v16, v16
	v_sub_f32_e32 v52, v169, v166
	v_cndmask_b32_e32 v54, 0, v16, vcc
	v_cmp_lt_f32_e32 vcc, s76, v17
	v_sub_f32_e32 v17, v17, v53
	v_exp_f32_e32 v17, v17
	v_add_f32_e32 v16, 0, v54
	v_cndmask_b32_e32 v55, 0, v17, vcc
	v_sub_f32_e32 v17, v18, v53
	v_exp_f32_e32 v17, v17
	v_cmp_lt_f32_e32 vcc, s76, v18
	v_add_f32_e32 v16, v55, v16
	s_nop 0
	v_cndmask_b32_e32 v194, 0, v17, vcc
	v_sub_f32_e32 v17, v19, v53
	v_exp_f32_e32 v17, v17
	v_cmp_lt_f32_e32 vcc, s76, v19
	v_add_f32_e32 v16, v194, v16
	s_nop 0
	v_cndmask_b32_e32 v195, 0, v17, vcc
	v_sub_f32_e32 v17, v20, v53
	v_exp_f32_e32 v17, v17
	v_cmp_lt_f32_e32 vcc, s76, v20
	v_add_f32_e32 v16, v195, v16
	s_nop 0
	v_cndmask_b32_e32 v196, 0, v17, vcc
	v_sub_f32_e32 v17, v21, v53
	v_exp_f32_e32 v17, v17
	v_cmp_lt_f32_e32 vcc, s76, v21
	v_add_f32_e32 v16, v196, v16
	s_nop 0
	v_cndmask_b32_e32 v197, 0, v17, vcc
	v_sub_f32_e32 v17, v22, v53
	v_exp_f32_e32 v17, v17
	v_cmp_lt_f32_e32 vcc, s76, v22
	v_add_f32_e32 v16, v197, v16
	s_nop 0
	v_cndmask_b32_e32 v198, 0, v17, vcc
	v_sub_f32_e32 v17, v23, v53
	v_exp_f32_e32 v17, v17
	v_cmp_lt_f32_e32 vcc, s76, v23
	v_add_f32_e32 v16, v198, v16
	s_nop 0
	v_cndmask_b32_e32 v199, 0, v17, vcc
	v_sub_f32_e32 v17, v24, v53
	v_exp_f32_e32 v17, v17
	v_cmp_lt_f32_e32 vcc, s76, v24
	v_add_f32_e32 v16, v199, v16
	s_nop 0
	v_cndmask_b32_e32 v174, 0, v17, vcc
	v_sub_f32_e32 v17, v25, v53
	v_exp_f32_e32 v17, v17
	v_cmp_lt_f32_e32 vcc, s76, v25
	v_add_f32_e32 v16, v174, v16
	s_nop 0
	v_cndmask_b32_e32 v176, 0, v17, vcc
	v_sub_f32_e32 v17, v26, v53
	v_exp_f32_e32 v17, v17
	v_cmp_lt_f32_e32 vcc, s76, v26
	v_add_f32_e32 v16, v176, v16
	s_nop 0
	v_cndmask_b32_e32 v178, 0, v17, vcc
	v_sub_f32_e32 v17, v27, v53
	v_exp_f32_e32 v17, v17
	v_cmp_lt_f32_e32 vcc, s76, v27
	v_add_f32_e32 v16, v178, v16
	s_nop 0
	v_cndmask_b32_e32 v180, 0, v17, vcc
	v_sub_f32_e32 v17, v28, v53
	v_exp_f32_e32 v17, v17
	v_cmp_lt_f32_e32 vcc, s76, v28
	v_add_f32_e32 v16, v180, v16
	s_nop 0
	v_cndmask_b32_e32 v183, 0, v17, vcc
	v_sub_f32_e32 v17, v29, v53
	v_exp_f32_e32 v17, v17
	v_cmp_lt_f32_e32 vcc, s76, v29
	v_add_f32_e32 v16, v183, v16
	s_nop 0
	v_cndmask_b32_e32 v185, 0, v17, vcc
	v_sub_f32_e32 v17, v30, v53
	v_exp_f32_e32 v17, v17
	v_cmp_lt_f32_e32 vcc, s76, v30
	v_add_f32_e32 v16, v185, v16
	s_nop 0
	v_cndmask_b32_e32 v187, 0, v17, vcc
	v_sub_f32_e32 v17, v31, v53
	v_exp_f32_e32 v17, v17
	v_cmp_lt_f32_e32 vcc, s76, v31
	v_add_f32_e32 v16, v187, v16
	s_nop 0
	v_cndmask_b32_e32 v189, 0, v17, vcc
	v_cmp_lt_f32_e32 vcc, s76, v0
	v_sub_f32_e32 v0, v0, v53
	v_exp_f32_e32 v0, v0
	v_add_f32_e32 v16, v189, v16
	v_cndmask_b32_e32 v170, 0, v0, vcc
	v_cmp_lt_f32_e32 vcc, s76, v1
	v_sub_f32_e32 v1, v1, v53
	v_exp_f32_e32 v1, v1
	v_add_f32_e32 v0, v170, v16
	v_cndmask_b32_e32 v171, 0, v1, vcc
	v_sub_f32_e32 v1, v2, v53
	v_exp_f32_e32 v1, v1
	v_cmp_lt_f32_e32 vcc, s76, v2
	v_add_f32_e32 v0, v171, v0
	s_nop 0
	v_cndmask_b32_e32 v172, 0, v1, vcc
	v_sub_f32_e32 v1, v3, v53
	v_exp_f32_e32 v1, v1
	v_cmp_lt_f32_e32 vcc, s76, v3
	v_add_f32_e32 v0, v172, v0
	s_nop 0
	v_cndmask_b32_e32 v173, 0, v1, vcc
	v_sub_f32_e32 v1, v4, v53
	v_exp_f32_e32 v1, v1
	v_cmp_lt_f32_e32 vcc, s76, v4
	v_add_f32_e32 v0, v173, v0
	s_nop 0
	v_cndmask_b32_e32 v175, 0, v1, vcc
	v_sub_f32_e32 v1, v5, v53
	v_exp_f32_e32 v1, v1
	v_cmp_lt_f32_e32 vcc, s76, v5
	v_add_f32_e32 v0, v175, v0
	s_nop 0
	v_cndmask_b32_e32 v177, 0, v1, vcc
	v_sub_f32_e32 v1, v6, v53
	v_exp_f32_e32 v1, v1
	v_cmp_lt_f32_e32 vcc, s76, v6
	v_add_f32_e32 v0, v177, v0
	s_nop 0
	v_cndmask_b32_e32 v179, 0, v1, vcc
	v_sub_f32_e32 v1, v7, v53
	v_exp_f32_e32 v1, v1
	v_cmp_lt_f32_e32 vcc, s76, v7
	v_add_f32_e32 v0, v179, v0
	s_nop 0
	v_cndmask_b32_e32 v181, 0, v1, vcc
	v_sub_f32_e32 v1, v8, v53
	v_exp_f32_e32 v1, v1
	v_cmp_lt_f32_e32 vcc, s76, v8
	v_add_f32_e32 v0, v181, v0
	s_nop 0
	v_cndmask_b32_e32 v182, 0, v1, vcc
	v_sub_f32_e32 v1, v9, v53
	v_exp_f32_e32 v1, v1
	v_cmp_lt_f32_e32 vcc, s76, v9
	v_add_f32_e32 v0, v182, v0
	s_nop 0
	v_cndmask_b32_e32 v184, 0, v1, vcc
	v_sub_f32_e32 v1, v10, v53
	v_exp_f32_e32 v1, v1
	v_cmp_lt_f32_e32 vcc, s76, v10
	v_add_f32_e32 v0, v184, v0
	s_nop 0
	v_cndmask_b32_e32 v186, 0, v1, vcc
	v_sub_f32_e32 v1, v11, v53
	v_exp_f32_e32 v1, v1
	v_cmp_lt_f32_e32 vcc, s76, v11
	v_add_f32_e32 v0, v186, v0
	s_nop 0
	v_cndmask_b32_e32 v188, 0, v1, vcc
	v_sub_f32_e32 v1, v12, v53
	v_exp_f32_e32 v1, v1
	v_cmp_lt_f32_e32 vcc, s76, v12
	v_add_f32_e32 v0, v188, v0
	s_nop 0
	v_cndmask_b32_e32 v190, 0, v1, vcc
	v_sub_f32_e32 v1, v13, v53
	v_exp_f32_e32 v1, v1
	v_cmp_lt_f32_e32 vcc, s76, v13
	v_add_f32_e32 v0, v190, v0
	s_nop 0
	v_cndmask_b32_e32 v191, 0, v1, vcc
	v_sub_f32_e32 v1, v14, v53
	v_exp_f32_e32 v1, v1
	v_cmp_lt_f32_e32 vcc, s76, v14
	v_exp_f32_e32 v14, v52
	v_cvt_pk_bf16_f32 v52, v54, v55
	v_cndmask_b32_e32 v192, 0, v1, vcc
	v_sub_f32_e32 v1, v15, v53
	v_cvt_pk_bf16_f32 v53, v194, v195
	v_cvt_pk_bf16_f32 v54, v196, v197
	s_nop 0
	v_pk_mul_f32 v[16:17], v[122:123], v[14:15] op_sel_hi:[1,0]
	v_pk_mul_f32 v[18:19], v[124:125], v[14:15] op_sel_hi:[1,0]
	v_pk_mul_f32 v[20:21], v[126:127], v[14:15] op_sel_hi:[1,0]
	v_pk_mul_f32 v[22:23], v[128:129], v[14:15] op_sel_hi:[1,0]
	v_pk_mul_f32 v[24:25], v[130:131], v[14:15] op_sel_hi:[1,0]
	v_pk_mul_f32 v[26:27], v[132:133], v[14:15] op_sel_hi:[1,0]
	v_pk_mul_f32 v[28:29], v[134:135], v[14:15] op_sel_hi:[1,0]
	v_pk_mul_f32 v[30:31], v[136:137], v[14:15] op_sel_hi:[1,0]
	v_cvt_pk_bf16_f32 v55, v198, v199
	v_exp_f32_e32 v1, v1
	v_add_f32_e32 v0, v191, v0
	s_waitcnt lgkmcnt(0)
; #define MFMA32(a, b, c) __builtin_amdgcn_mfma_f32_32x32x16_bf16((a), (b), (c), 0, 0, 0)
; template <int KSTRIDE, bool WIN, int MASK, int MODE>
; DI void attend_tile(const u16* Ks, const u16* Vts, const bf16x8 (&qf)[4], f32x16 (&O)[2], float& m, float& l, int dbase,
;                     float slope2, bool lanesel, float invl, unsigned* imp_row, int mbase, int lr, int hh) {
;     ...
;   for (int kt = 0; kt < 2; ++kt) {
; #pragma unroll
;     for (int e = 0; e < 16; ++e) s[kt][e] = 0.f;
; #pragma unroll
;     for (int ks = 0; ks < 4; ++ks) {
;       bf16x8 a = *(const bf16x8*)(Ks + (kt * 32 + lr) * 72 + ks * 16 + hh * 8);
;       s[kt] = MFMA32(a, qf[ks], s[kt]);
;     }
;   }
;   const float fd0 = (float)(dbase - KSTRIDE * 4 * hh);
;   const float ct = slope2 * fd0;
;   float mx = -1e30f;
; #pragma unroll
;   for (int kt = 0; kt < 2; ++kt)
; #pragma unroll
;     for (int e = 0; e < 16; ++e) {
;       const float Ke = (float)(KSTRIDE * (kt * 32 + (e & 3) + 8 * (e >> 2)));
;       float v = fmaf(slope2, Ke, s[kt][e]);
;       if (MASK == 1) {
;         const float fd = fd0 - Ke;
;         bool valid = fd >= 0.f;
;         if (WIN) valid = valid && (fd < 512.f);
;         valid = valid && lanesel;
;         v = valid ? v : -1e30f;
;       }
;       s[kt][e] = v;
;       mx = fmaxf(mx, v);
;     ...
; #pragma unroll
;   for (int kt = 0; kt < 2; ++kt)
; #pragma unroll
;     for (int sx = 0; sx < 2; ++sx) {
;       unsigned pk[4];
; #pragma unroll
;       for (int q = 0; q < 4; ++q) pk[q] = pack2(s[kt][8 * sx + 2 * q], s[kt][8 * sx + 2 * q + 1]);
;       bf16x8 pb;
;       {
;         u32x4 t4 = {pk[0], pk[1], pk[2], pk[3]};
;         pb = __builtin_bit_cast(bf16x8, t4);
;       }
; #pragma unroll
;       for (int dt = 0; dt < 2; ++dt) {
;         bf16x8 a = *(const bf16x8*)(Vts + (dt * 32 + lr) * 72 + kt * 32 + 16 * sx + 8 * hh);
;         O[dt] = MFMA32(a, pb, O[dt]);
;       }
;     }
	v_mfma_f32_32x32x16_bf16 v[16:31], v[200:203], v[52:55], v[16:31]
	s_nop 0
	v_cmp_lt_f32_e32 vcc, s76, v15
	v_add_f32_e32 v0, v192, v0
	v_mul_f32_e64 v2, v140, v14
	v_mul_f32_e64 v3, v141, v14
	v_cndmask_b32_e32 v193, 0, v1, vcc
	v_add_f32_e32 v167, v193, v0
	v_fmac_f32_e32 v167, v168, v14
	v_pk_mul_f32 v[0:1], v[138:139], v[14:15] op_sel_hi:[1,0]
	v_pk_mul_f32 v[4:5], v[142:143], v[14:15] op_sel_hi:[1,0]
	v_pk_mul_f32 v[6:7], v[144:145], v[14:15] op_sel_hi:[1,0]
	v_pk_mul_f32 v[8:9], v[146:147], v[14:15] op_sel_hi:[1,0]
	v_pk_mul_f32 v[10:11], v[148:149], v[14:15] op_sel_hi:[1,0]
	v_pk_mul_f32 v[12:13], v[150:151], v[14:15] op_sel_hi:[1,0]
	v_pk_mul_f32 v[14:15], v[152:153], v[14:15] op_sel_hi:[1,0]
	s_mov_b64 vcc, 0
	s_waitcnt lgkmcnt(0)
	v_mfma_f32_32x32x16_bf16 v[0:15], v[204:207], v[52:55], v[0:15]
	s_nop 0
	v_cvt_pk_bf16_f32 v52, v174, v176
	v_cvt_pk_bf16_f32 v53, v178, v180
	v_cvt_pk_bf16_f32 v54, v183, v185
	v_cvt_pk_bf16_f32 v55, v187, v189
	s_waitcnt lgkmcnt(0)
	s_nop 0
	v_mfma_f32_32x32x16_bf16 v[16:31], v[214:217], v[52:55], v[16:31]
	s_nop 0
	s_waitcnt lgkmcnt(0)
	v_mfma_f32_32x32x16_bf16 v[0:15], v[218:221], v[52:55], v[0:15]
	v_cvt_pk_bf16_f32 v52, v170, v171
	v_cvt_pk_bf16_f32 v53, v172, v173
	s_nop 0
	v_cvt_pk_bf16_f32 v54, v175, v177
	v_cvt_pk_bf16_f32 v55, v179, v181
	s_waitcnt lgkmcnt(0)
	s_nop 0
	v_mfma_f32_32x32x16_bf16 v[16:31], v[222:225], v[52:55], v[16:31]
	s_nop 0
	s_waitcnt lgkmcnt(0)
	v_mfma_f32_32x32x16_bf16 v[0:15], v[226:229], v[52:55], v[0:15]
	s_nop 0
	v_cvt_pk_bf16_f32 v52, v182, v184
	v_cvt_pk_bf16_f32 v53, v186, v188
	v_cvt_pk_bf16_f32 v54, v190, v191
	v_cvt_pk_bf16_f32 v55, v192, v193
	s_waitcnt lgkmcnt(0)
	s_nop 0
	v_mfma_f32_32x32x16_bf16 v[16:31], v[230:233], v[52:55], v[16:31]
	s_nop 0
	s_waitcnt lgkmcnt(0)
	v_mfma_f32_32x32x16_bf16 v[0:15], v[234:237], v[52:55], v[0:15]
	s_nop 7
	s_nop 3
.LBB0_644:
	s_andn2_b64 vcc, exec, vcc
	s_cbranch_vccnz .LBB0_646
	s_waitcnt lgkmcnt(4)
	v_mfma_f32_32x32x16_bf16 v[16:31], v[48:51], v[64:67], 0
	s_lshl_b32 s80, s80, 6
	s_waitcnt lgkmcnt(3)
	v_mfma_f32_32x32x16_bf16 v[16:31], v[44:47], v[68:71], v[16:31]
	s_waitcnt lgkmcnt(2)
	v_mfma_f32_32x32x16_bf16 v[16:31], v[32:35], v[72:75], v[16:31]
	s_waitcnt lgkmcnt(0)
	v_mfma_f32_32x32x16_bf16 v[0:15], v[40:43], v[64:67], 0
	v_mfma_f32_32x32x16_bf16 v[16:31], v[36:39], v[76:79], v[16:31]
	ds_read_b128 v[32:35], v165 offset:4640
	ds_read_b128 v[36:39], v165 offset:4672
	s_waitcnt lgkmcnt(1)
	v_mfma_f32_32x32x16_bf16 v[0:15], v[32:35], v[68:71], v[0:15]
	ds_read_b128 v[32:35], v165 offset:4704
	s_nop 6
	v_fma_f32 v16, 0, v106, v16
	v_add_f32_e32 v17, v106, v17
	v_fma_f32 v18, 2.0, v106, v18
	v_fmamk_f32 v19, v106, 0x40400000, v19
	v_fmamk_f32 v20, v106, 0x41000000, v20
	v_fmamk_f32 v21, v106, 0x41100000, v21
	s_waitcnt lgkmcnt(1)
	v_mfma_f32_32x32x16_bf16 v[0:15], v[36:39], v[72:75], v[0:15]
	v_fmamk_f32 v22, v106, 0x41200000, v22
	v_fmamk_f32 v23, v106, 0x41300000, v23
	v_fmamk_f32 v24, v106, 0x41800000, v24
	v_fmamk_f32 v25, v106, 0x41880000, v25
	v_fmamk_f32 v26, v106, 0x41900000, v26
	v_fmamk_f32 v27, v106, 0x41980000, v27
	v_fmamk_f32 v28, v106, 0x41c00000, v28
	s_waitcnt lgkmcnt(0)
	v_mfma_f32_32x32x16_bf16 v[0:15], v[32:35], v[76:79], v[0:15]
	ds_read_b128 v[200:203], v165 offset:9216
	ds_read_b128 v[204:207], v165 offset:13824
	ds_read_b128 v[214:217], v165 offset:9248
	ds_read_b128 v[218:221], v165 offset:13856
	ds_read_b128 v[222:225], v165 offset:9280
	ds_read_b128 v[226:229], v165 offset:13888
	ds_read_b128 v[230:233], v165 offset:9312
	ds_read_b128 v[234:237], v165 offset:13920
	v_max3_f32 v33, v16, s95, v17
	v_max3_f32 v33, v33, v18, v19
	v_max3_f32 v33, v33, v20, v21
	v_max3_f32 v33, v33, v22, v23
	v_max3_f32 v33, v33, v24, v25
	v_max3_f32 v33, v33, v26, v27
	v_fmamk_f32 v29, v106, 0x41c80000, v29
	v_max3_f32 v33, v33, v28, v29
	v_fmamk_f32 v30, v106, 0x41d00000, v30
	v_fmac_f32_e32 v31, 0x41d80000, v106
	v_max3_f32 v33, v33, v30, v31
	s_nop 0
	v_fmamk_f32 v0, v106, 0x42000000, v0
	v_fmamk_f32 v1, v106, 0x42040000, v1
	v_max3_f32 v33, v33, v0, v1
	v_fmamk_f32 v2, v106, 0x42080000, v2
	v_fmamk_f32 v3, v106, 0x420c0000, v3
	v_max3_f32 v33, v33, v2, v3
	v_fmamk_f32 v4, v106, 0x42200000, v4
	v_fmamk_f32 v5, v106, 0x42240000, v5
	v_max3_f32 v33, v33, v4, v5
	v_fmamk_f32 v6, v106, 0x42280000, v6
	v_fmamk_f32 v7, v106, 0x422c0000, v7
	v_subrev_u32_e32 v32, s80, v57
	v_max3_f32 v33, v33, v6, v7
	v_fmamk_f32 v8, v106, 0x42400000, v8
	v_fmamk_f32 v9, v106, 0x42440000, v9
	v_cvt_f32_i32_e32 v32, v32
	v_max3_f32 v33, v33, v8, v9
	v_fmamk_f32 v10, v106, 0x42480000, v10
	v_fmamk_f32 v11, v106, 0x424c0000, v11
	v_max3_f32 v33, v33, v10, v11
	v_fmamk_f32 v12, v106, 0x42600000, v12
	v_fmamk_f32 v13, v106, 0x42640000, v13
	v_max3_f32 v33, v33, v12, v13
	v_fmamk_f32 v14, v106, 0x42680000, v14
	v_fmac_f32_e32 v15, 0x426c0000, v106
	v_max3_f32 v33, v33, v14, v15
	v_cmp_lt_f32_e32 vcc, s76, v33
	v_fma_f32 v33, -v106, v32, v33
	s_nop 0
	v_cndmask_b32_e32 v33, v160, v33, vcc
	v_mov_b32_e32 v34, v33
	s_nop 1
	v_permlane32_swap_b32_e32 v34, v33
	s_nop 1
	s_waitcnt lgkmcnt(0)
; #define MFMA32(a, b, c) __builtin_amdgcn_mfma_f32_32x32x16_bf16((a), (b), (c), 0, 0, 0)
; template <int KSTRIDE, bool WIN, int MASK, int MODE>
; DI void attend_tile(const u16* Ks, const u16* Vts, const bf16x8 (&qf)[4], f32x16 (&O)[2], float& m, float& l, int dbase,
;                     float slope2, bool lanesel, float invl, unsigned* imp_row, int mbase, int lr, int hh) {
;     ...
;   mx = (mx > -1e29f) ? mx - ct : -1e30f;
;   mx = fmaxf(mx, __shfl_xor(mx, 32));
;   if (MASK == 2) mx = lanesel ? mx : -1e30f;
;   float mnew = m, alpha = 1.f;
;   if (MODE != 2) {
;     mnew = fmaxf(m, mx);
;     alpha = fexp2(m - mnew);
;     m = mnew;
;   }
;   float shift = mnew + ct;
;   if (MASK == 2) shift = lanesel ? shift : 1e30f;
;   float rs = 0.f;
; #pragma unroll
;   for (int kt = 0; kt < 2; ++kt)
; #pragma unroll
;     for (int e = 0; e < 16; ++e) {
;       float v = s[kt][e];
;       float pv;
;       if (MASK == 1) pv = (v > -1e29f) ? fexp2(v - shift) : 0.f;
;       else pv = fexp2(v - shift);
;       if (MODE == 2) pv *= invl;
;       s[kt][e] = pv;
;       rs += pv;
;     }
;   if (MODE != 2) l = l * alpha + rs;
;   if (MODE == 1) return;
;   if (MODE == 0) {
; #pragma unroll
;     for (int e = 0; e < 16; ++e) { O[0][e] *= alpha; O[1][e] *= alpha; }
;   }
;   if (MODE == 2) {
; #pragma unroll
;     for (int kt = 0; kt < 2; ++kt)
; #pragma unroll
;       for (int q4 = 0; q4 < 4; ++q4) {
;         float qsum = s[kt][q4 * 4] + s[kt][q4 * 4 + 1] + s[kt][q4 * 4 + 2] + s[kt][q4 * 4 + 3];
;         float last = s[kt][q4 * 4 + 3];
;         int mi = mbase + kt * 8 + 2 * q4 + hh;
;         atomicAdd(imp_row + mi, (unsigned)(qsum * 1048576.f + 0.5f));
;         if (mi + 1 < 64) atomicAdd(imp_row + mi + 1, (unsigned)(last * 1048576.f + 0.5f));
;       }
;   }
; #pragma unroll
;   for (int kt = 0; kt < 2; ++kt)
; #pragma unroll
;     for (int sx = 0; sx < 2; ++sx) {
;       unsigned pk[4];
; #pragma unroll
;       for (int q = 0; q < 4; ++q) pk[q] = pack2(s[kt][8 * sx + 2 * q], s[kt][8 * sx + 2 * q + 1]);
;       bf16x8 pb;
;       {
;         u32x4 t4 = {pk[0], pk[1], pk[2], pk[3]};
;         pb = __builtin_bit_cast(bf16x8, t4);
;       }
; #pragma unroll
;       for (int dt = 0; dt < 2; ++dt) {
;         bf16x8 a = *(const bf16x8*)(Vts + (dt * 32 + lr) * 72 + kt * 32 + 16 * sx + 8 * hh);
;         O[dt] = MFMA32(a, pb, O[dt]);
;       }
;     }
	v_max_f32_e32 v34, v34, v34
	v_max_f32_e32 v33, v33, v34
	v_cndmask_b32_e64 v33, v160, v33, s[0:1]
	v_max_f32_e32 v34, v169, v169
	v_max_f32_e32 v166, v34, v33
	v_fma_f32 v32, v106, v32, v166
	v_cndmask_b32_e64 v32, v155, v32, s[0:1]
	v_sub_f32_e32 v16, v16, v32
	v_exp_f32_e32 v34, v16
	v_sub_f32_e32 v17, v17, v32
	v_exp_f32_e32 v35, v17
	v_sub_f32_e32 v17, v18, v32
	v_exp_f32_e32 v173, v17
	v_sub_f32_e32 v17, v19, v32
	v_exp_f32_e32 v174, v17
	v_sub_f32_e32 v17, v20, v32
	v_sub_f32_e32 v1, v1, v32
	v_add_f32_e32 v16, 0, v34
	v_exp_f32_e32 v175, v17
	v_sub_f32_e32 v17, v21, v32
	v_exp_f32_e32 v37, v1
	v_sub_f32_e32 v1, v2, v32
	v_add_f32_e32 v16, v35, v16
	v_exp_f32_e32 v176, v17
	v_sub_f32_e32 v17, v22, v32
	v_exp_f32_e32 v38, v1
	v_sub_f32_e32 v1, v3, v32
	v_add_f32_e32 v16, v173, v16
	v_exp_f32_e32 v177, v17
	v_sub_f32_e32 v17, v23, v32
	v_exp_f32_e32 v39, v1
	v_sub_f32_e32 v1, v4, v32
	v_add_f32_e32 v16, v174, v16
	v_exp_f32_e32 v178, v17
	v_sub_f32_e32 v17, v24, v32
	v_exp_f32_e32 v40, v1
	v_sub_f32_e32 v1, v5, v32
	v_add_f32_e32 v16, v175, v16
	v_exp_f32_e32 v51, v17
	v_sub_f32_e32 v17, v25, v32
	v_exp_f32_e32 v41, v1
	v_sub_f32_e32 v1, v6, v32
	v_add_f32_e32 v16, v176, v16
	v_exp_f32_e32 v53, v17
	v_sub_f32_e32 v17, v26, v32
	v_exp_f32_e32 v42, v1
	v_sub_f32_e32 v1, v7, v32
	v_add_f32_e32 v16, v177, v16
	v_exp_f32_e32 v54, v17
	v_sub_f32_e32 v17, v27, v32
	v_exp_f32_e32 v44, v1
	v_sub_f32_e32 v1, v8, v32
	v_add_f32_e32 v16, v178, v16
	v_exp_f32_e32 v55, v17
	v_sub_f32_e32 v17, v28, v32
	v_exp_f32_e32 v43, v1
	v_sub_f32_e32 v1, v9, v32
	v_sub_f32_e32 v33, v169, v166
	v_add_f32_e32 v16, v51, v16
	v_exp_f32_e32 v169, v17
	v_sub_f32_e32 v17, v29, v32
	v_exp_f32_e32 v45, v1
	v_sub_f32_e32 v1, v10, v32
	v_add_f32_e32 v16, v53, v16
	v_exp_f32_e32 v170, v17
	v_sub_f32_e32 v17, v30, v32
	v_exp_f32_e32 v46, v1
	v_sub_f32_e32 v1, v11, v32
	v_add_f32_e32 v16, v54, v16
	v_exp_f32_e32 v171, v17
	v_sub_f32_e32 v17, v31, v32
	v_exp_f32_e32 v47, v1
	v_sub_f32_e32 v1, v12, v32
	v_add_f32_e32 v16, v55, v16
	v_exp_f32_e32 v172, v17
	v_sub_f32_e32 v0, v0, v32
	v_exp_f32_e32 v48, v1
	v_sub_f32_e32 v1, v13, v32
	v_add_f32_e32 v16, v169, v16
	v_exp_f32_e32 v36, v0
	v_exp_f32_e32 v49, v1
	v_sub_f32_e32 v1, v14, v32
	v_exp_f32_e32 v14, v33
	v_add_f32_e32 v16, v170, v16
	v_add_f32_e32 v16, v171, v16
	v_add_f32_e32 v16, v172, v16
	v_add_f32_e32 v0, v36, v16
	v_pk_mul_f32 v[16:17], v[122:123], v[14:15] op_sel_hi:[1,0]
	v_pk_mul_f32 v[18:19], v[124:125], v[14:15] op_sel_hi:[1,0]
	s_nop 0
	v_add_f32_e32 v0, v37, v0
	v_add_f32_e32 v0, v38, v0
	v_add_f32_e32 v0, v39, v0
	v_add_f32_e32 v0, v40, v0
	v_add_f32_e32 v0, v41, v0
	v_add_f32_e32 v0, v42, v0
	v_add_f32_e32 v0, v44, v0
	v_exp_f32_e32 v50, v1
	v_sub_f32_e32 v1, v15, v32
	v_pk_mul_f32 v[20:21], v[126:127], v[14:15] op_sel_hi:[1,0]
	v_pk_mul_f32 v[22:23], v[128:129], v[14:15] op_sel_hi:[1,0]
	v_pk_mul_f32 v[24:25], v[130:131], v[14:15] op_sel_hi:[1,0]
	v_pk_mul_f32 v[26:27], v[132:133], v[14:15] op_sel_hi:[1,0]
	v_pk_mul_f32 v[28:29], v[134:135], v[14:15] op_sel_hi:[1,0]
	v_pk_mul_f32 v[30:31], v[136:137], v[14:15] op_sel_hi:[1,0]
	v_cvt_pk_bf16_f32 v32, v34, v35
	v_cvt_pk_bf16_f32 v33, v173, v174
	v_cvt_pk_bf16_f32 v34, v175, v176
	v_cvt_pk_bf16_f32 v35, v177, v178
	v_add_f32_e32 v0, v43, v0
	v_add_f32_e32 v0, v45, v0
	s_waitcnt lgkmcnt(0)
	v_mfma_f32_32x32x16_bf16 v[16:31], v[200:203], v[32:35], v[16:31]
	s_nop 0
	v_add_f32_e32 v0, v46, v0
	v_add_f32_e32 v0, v47, v0
	v_exp_f32_e32 v52, v1
	v_add_f32_e32 v0, v48, v0
	v_add_f32_e32 v0, v49, v0
	v_add_f32_e32 v0, v50, v0
	v_add_f32_e32 v167, v52, v0
	v_fmac_f32_e32 v167, v168, v14
	v_pk_mul_f32 v[0:1], v[138:139], v[14:15] op_sel_hi:[1,0]
	v_pk_mul_f32 v[2:3], v[140:141], v[14:15] op_sel_hi:[1,0]
	v_pk_mul_f32 v[4:5], v[142:143], v[14:15] op_sel_hi:[1,0]
	v_pk_mul_f32 v[6:7], v[144:145], v[14:15] op_sel_hi:[1,0]
	v_pk_mul_f32 v[8:9], v[146:147], v[14:15] op_sel_hi:[1,0]
	v_pk_mul_f32 v[10:11], v[148:149], v[14:15] op_sel_hi:[1,0]
	v_pk_mul_f32 v[12:13], v[150:151], v[14:15] op_sel_hi:[1,0]
	v_pk_mul_f32 v[14:15], v[152:153], v[14:15] op_sel_hi:[1,0]
	s_waitcnt lgkmcnt(0)
	s_nop 0
	v_mfma_f32_32x32x16_bf16 v[0:15], v[204:207], v[32:35], v[0:15]
	s_nop 0
	v_cvt_pk_bf16_f32 v32, v51, v53
	v_cvt_pk_bf16_f32 v33, v54, v55
	v_cvt_pk_bf16_f32 v34, v169, v170
	v_cvt_pk_bf16_f32 v35, v171, v172
	s_waitcnt lgkmcnt(0)
	s_nop 0
	v_mfma_f32_32x32x16_bf16 v[16:31], v[214:217], v[32:35], v[16:31]
	s_nop 0
	s_waitcnt lgkmcnt(0)
	v_mfma_f32_32x32x16_bf16 v[0:15], v[218:221], v[32:35], v[0:15]
	v_cvt_pk_bf16_f32 v32, v36, v37
	v_cvt_pk_bf16_f32 v33, v38, v39
	s_nop 0
	v_cvt_pk_bf16_f32 v34, v40, v41
	v_cvt_pk_bf16_f32 v35, v42, v44
	s_waitcnt lgkmcnt(0)
	s_nop 0
	v_mfma_f32_32x32x16_bf16 v[16:31], v[222:225], v[32:35], v[16:31]
	s_nop 0
	s_waitcnt lgkmcnt(0)
	v_mfma_f32_32x32x16_bf16 v[0:15], v[226:229], v[32:35], v[0:15]
	s_nop 0
	v_cvt_pk_bf16_f32 v32, v43, v45
	v_cvt_pk_bf16_f32 v33, v46, v47
	v_cvt_pk_bf16_f32 v34, v48, v49
	v_cvt_pk_bf16_f32 v35, v50, v52
	s_waitcnt lgkmcnt(0)
	s_nop 0
	v_mfma_f32_32x32x16_bf16 v[16:31], v[230:233], v[32:35], v[16:31]
	s_nop 0
	s_waitcnt lgkmcnt(0)
	v_mfma_f32_32x32x16_bf16 v[0:15], v[234:237], v[32:35], v[0:15]
	s_nop 7
	s_nop 3
